# hand-written S5 mixer task: operand loads pipelined three K-steps ahead, rolling LDS prefetch in the carry scan, all epilogue loads issued before the scan
# baseline (speedup 1.0000x reference)
; #define LAS __attribute__((address_space(3)))
; #define KPTR(T, ap64, i) ((T*)(__attribute__((address_space(1))) T*)(ap64)[i])
; DEV void s5_task(int l, int b, int g, int wave, int lane, LAS unsigned char* sm, unsigned char* ws, float* out, const float* dskip) {
;     const int lg = l * 16 + g, fr = lane & 15, fq = lane >> 4;
;     const bf16_t* TQ = (const bf16_t*)(ws + WS_S5 + (size_t)lg * S5_SIZE + S5_TQ); const bf16_t* PM = (const bf16_t*)(ws + WS_S5 + (size_t)lg * S5_SIZE + S5_P);
;     const bf16_t* U = (const bf16_t*)(ws + WS_U5) + ((size_t)g * M + (size_t)b * SEQ) * 16;
;     LAS float* Hloc = (LAS float*)sm; LAS bf16_t* Hin = (LAS bf16_t*)(sm + 32768);
;     f32x4 acc[5][4];
; #pragma unroll
;     for (int i = 0; i < 5; ++i)
; #pragma unroll
;         for (int nt = 0; nt < 4; ++nt) acc[i][nt] = (f32x4){0.f, 0.f, 0.f, 0.f};
;     __syncthreads();
; #pragma unroll 4
;     for (int s = 0; s < 16; ++s) { const int k0 = 32 * s + 8 * fq;
;         bf16x8 bfr[4];
; #pragma unroll
;         for (int nt = 0; nt < 4; ++nt) bfr[nt] = *(const bf16x8*)(U + (size_t)(nt * 16 + fr) * 512 + k0);
; __global__ void __launch_bounds__(512, 2) mk_fwd(MKArgs args) {
;     ...
;             for (int r2_ = 0; r2_ < REP_S5 + REP_PREP - 1; ++r2_) { PHASE_IDS if (r2_ == 0 || REP_S5 > 1) for (int k = (2 * G - 33 - bx) % G; k < NB * 16; k += G) s5_task(l, k >> 4, k & 15, wave, lane, ldsl + RING_OFF, ws, out, KPTR(const float, ap, 17));
.LBB0_974:
	v_readlane_b32 s2, v255, 0
	s_lshl_b32 s23, s2, 4
	s_lshl_b32 s1, s0, 1
	v_readlane_b32 s2, v254, 58
	s_sub_i32 s1, s1, s2
	s_sub_i32 s1, s1, 33
	s_add_u32 s88, s26, 0x5b00000
	s_addc_u32 s89, s27, 0
	s_abs_i32 s4, s0
	v_cvt_f32_u32_e32 v0, s4
	s_sub_i32 s6, 0, s4
	s_ashr_i32 s14, s1, 31
	s_abs_i32 s1, s1
	v_rcp_iflag_f32_e32 v0, v0
	v_readlane_b32 s5, v254, 3
	v_mbcnt_lo_u32_b32 v2, -1, 0
	v_mbcnt_hi_u32_b32 v2, -1, v2
	s_mov_b32 s85, 0x30c30c31
	v_mul_f32_e32 v0, 0x4f7ffffe, v0
	v_cvt_u32_f32_e32 v0, v0
	v_add_u32_e32 v114, s5, v2
	v_readlane_b32 s3, v255, 1
	v_readfirstlane_b32 s7, v0
	s_mul_i32 s6, s6, s7
	s_mul_hi_u32 s6, s7, s6
	s_add_i32 s7, s7, s6
	s_mul_hi_u32 s6, s1, s7
	s_mul_i32 s6, s6, s4
	s_sub_i32 s1, s1, s6
	s_sub_i32 s6, s1, s4
	s_cmp_ge_u32 s1, s4
	s_cselect_b32 s1, s6, s1
	s_sub_i32 s6, s1, s4
	s_cmp_ge_u32 s1, s4
	s_cselect_b32 s1, s6, s1
	s_xor_b32 s15, s1, s14
	v_and_b32_e32 v116, 63, v114
	s_sub_i32 s20, s15, s14
	v_readfirstlane_b32 s5, v114
	s_cmpk_lt_i32 s20, 0x80
	v_and_b32_e32 v118, 15, v114
	v_lshlrev_b32_e32 v120, 3, v116
	s_cbranch_scc0 .LBB0_1023
	s_ashr_i32 s4, s5, 6
	v_readlane_b32 s22, v254, 46
	v_readlane_b32 s2, v254, 50
	v_readlane_b32 s3, v254, 51
	v_readlane_b32 s6, v255, 2
	s_load_dwordx2 s[16:17], s[2:3], 0x88
	s_waitcnt lgkmcnt(0)
	s_lshl_b32 s6, s6, 2
	s_add_u32 s16, s16, s6
	s_addc_u32 s17, s17, 0
.Ls5s_task:
	v_lshrrev_b32_e32 v0, 4, v116
	v_lshlrev_b32_e32 v220, 4, v0
	v_lshl_add_u32 v198, v118, 10, v220
	v_add_u32_e32 v199, 0x4000, v198
	v_add_u32_e32 v200, 0x8000, v198
	v_add_u32_e32 v201, 0xc000, v198
	s_lshl_b32 s1, s4, 14
	v_add_u32_e32 v202, s1, v198
	v_add_u32_e32 v203, 0x20000, v202
	v_add_u32_e32 v204, 0x40000, v202
	v_add_u32_e32 v205, 0x60000, v202
	v_add_u32_e32 v206, 0x80000, v202
	v_lshl_add_u32 v207, v118, 8, v220
	s_lshl_b32 s1, s4, 12
	v_add_u32_e32 v207, s1, v207
	v_add_u32_e32 v208, 0x8000, v207
	v_add_u32_e32 v209, 0x10000, v207
	v_add_u32_e32 v210, 0x18000, v207
	v_lshl_add_u32 v215, v118, 9, v220
	s_lshl_b32 s1, s4, 6
	s_add_i32 s1, s1, s96
	v_add_u32_e32 v215, s1, v215
	s_add_i32 s1, s96, 0x8000
	v_lshl_add_u32 v216, v116, 1, s1
	v_lshl_add_u32 v217, v116, 2, s96
	v_lshl_add_u32 v218, v118, 8, v220
	v_add_u32_e32 v218, s1, v218
	v_lshlrev_b32_e32 v220, 3, v0
	v_lshl_add_u32 v211, v118, 10, v220
	s_lshl_b32 s1, s4, 5
	v_add_u32_e32 v211, s1, v211
	v_add_u32_e32 v212, 0x4000, v211
	v_add_u32_e32 v213, 0x8000, v211
	v_add_u32_e32 v214, 0xc000, v211
	v_lshl_add_u32 v219, v118, 14, v220
	s_lshl_b32 s1, s4, 9
	v_add_u32_e32 v219, s1, v219
	s_add_i32 s8, s4, 0
	s_lshr_b32 s8, s8, 1
	s_add_i32 s9, s4, 8
	s_lshr_b32 s9, s9, 1
	s_add_i32 s10, s4, 16
	s_lshr_b32 s10, s10, 1
	s_add_i32 s11, s4, 24
	s_lshr_b32 s11, s11, 1
	s_and_b32 s1, s20, 15
	s_lshr_b32 s2, s20, 4
	s_add_i32 s3, s22, s1
	s_mul_i32 s3, s3, 0xc2400
	s_add_u32 s12, s26, s3
	s_addc_u32 s13, s27, 0
	s_add_u32 s12, s12, 0x5b02400
	s_addc_u32 s13, s13, 0
	s_add_u32 s18, s12, 0xa0000
	s_addc_u32 s19, s13, 0
	s_lshl_b32 s3, s1, 19
	s_lshl_b32 s6, s2, 16
	s_add_i32 s3, s3, s6
	s_add_u32 s14, s26, s3
	s_addc_u32 s15, s27, 0
	s_add_u32 s14, s14, 0xadd8100
	s_addc_u32 s15, s15, 0
	v_mov_b32_e32 v2, 0
	v_mov_b32_e32 v3, 0
	v_mov_b32_e32 v4, 0
	v_mov_b32_e32 v5, 0
	v_mov_b32_e32 v6, 0
	v_mov_b32_e32 v7, 0
	v_mov_b32_e32 v8, 0
	v_mov_b32_e32 v9, 0
	v_mov_b32_e32 v10, 0
	v_mov_b32_e32 v11, 0
	v_mov_b32_e32 v12, 0
	v_mov_b32_e32 v13, 0
	v_mov_b32_e32 v14, 0
	v_mov_b32_e32 v15, 0
	v_mov_b32_e32 v16, 0
	v_mov_b32_e32 v17, 0
	v_mov_b32_e32 v18, 0
	v_mov_b32_e32 v19, 0
	v_mov_b32_e32 v20, 0
	v_mov_b32_e32 v21, 0
	v_mov_b32_e32 v22, 0
	v_mov_b32_e32 v23, 0
	v_mov_b32_e32 v24, 0
	v_mov_b32_e32 v25, 0
	v_mov_b32_e32 v26, 0
	v_mov_b32_e32 v27, 0
	v_mov_b32_e32 v28, 0
	v_mov_b32_e32 v29, 0
	v_mov_b32_e32 v30, 0
	v_mov_b32_e32 v31, 0
	v_mov_b32_e32 v32, 0
	v_mov_b32_e32 v33, 0
	v_mov_b32_e32 v34, 0
	v_mov_b32_e32 v35, 0
	v_mov_b32_e32 v36, 0
	v_mov_b32_e32 v37, 0
	v_mov_b32_e32 v38, 0
	v_mov_b32_e32 v39, 0
	v_mov_b32_e32 v40, 0
	v_mov_b32_e32 v41, 0
	v_mov_b32_e32 v42, 0
	v_mov_b32_e32 v43, 0
	v_mov_b32_e32 v44, 0
	v_mov_b32_e32 v45, 0
	v_mov_b32_e32 v46, 0
	v_mov_b32_e32 v47, 0
	v_mov_b32_e32 v48, 0
	v_mov_b32_e32 v49, 0
	v_mov_b32_e32 v50, 0
	v_mov_b32_e32 v51, 0
	v_mov_b32_e32 v52, 0
	v_mov_b32_e32 v53, 0
	v_mov_b32_e32 v54, 0
	v_mov_b32_e32 v55, 0
	v_mov_b32_e32 v56, 0
	v_mov_b32_e32 v57, 0
	v_mov_b32_e32 v58, 0
	v_mov_b32_e32 v59, 0
	v_mov_b32_e32 v60, 0
	v_mov_b32_e32 v61, 0
	v_mov_b32_e32 v62, 0
	v_mov_b32_e32 v63, 0
	v_mov_b32_e32 v64, 0
	v_mov_b32_e32 v65, 0
	v_mov_b32_e32 v66, 0
	v_mov_b32_e32 v67, 0
	v_mov_b32_e32 v68, 0
	v_mov_b32_e32 v69, 0
	v_mov_b32_e32 v70, 0
	v_mov_b32_e32 v71, 0
	v_mov_b32_e32 v72, 0
	v_mov_b32_e32 v73, 0
	v_mov_b32_e32 v74, 0
	v_mov_b32_e32 v75, 0
	v_mov_b32_e32 v76, 0
	v_mov_b32_e32 v77, 0
	v_mov_b32_e32 v78, 0
	v_mov_b32_e32 v79, 0
	v_mov_b32_e32 v80, 0
	v_mov_b32_e32 v81, 0
	s_waitcnt lgkmcnt(0)
	s_barrier
; DEV void s5_task(int l, int b, int g, int wave, int lane, LAS unsigned char* sm, unsigned char* ws, float* out, const float* dskip) {
;     ...
;     for (int s = 0; s < 16; ++s) { const int k0 = 32 * s + 8 * fq;
;         bf16x8 bfr[4];
; #pragma unroll
;         for (int nt = 0; nt < 4; ++nt) bfr[nt] = *(const bf16x8*)(U + (size_t)(nt * 16 + fr) * 512 + k0);
; #pragma unroll
;         for (int i = 0; i < 4; ++i) { const int rt = wave + 8 * i;
;             if (2 * s <= rt) { const bf16x8 a = *(const bf16x8*)(TQ + (size_t)(rt * 16 + fr) * 512 + k0);
; #pragma unroll
;                 for (int nt = 0; nt < 4; ++nt) acc[i][nt] = __builtin_amdgcn_mfma_f32_16x16x32_bf16(a, bfr[nt], acc[i][nt], 0, 0, 0); } }
;         { const bf16x8 a = *(const bf16x8*)(TQ + (size_t)((32 + wave) * 16 + fr) * 512 + k0);
; #pragma unroll
;             for (int nt = 0; nt < 4; ++nt) acc[4][nt] = __builtin_amdgcn_mfma_f32_16x16x32_bf16(a, bfr[nt], acc[4][nt], 0, 0, 0); }
;     }
	global_load_dwordx4 v[122:125], v198, s[14:15]
	global_load_dwordx4 v[126:129], v199, s[14:15]
	global_load_dwordx4 v[130:133], v200, s[14:15]
	global_load_dwordx4 v[134:137], v201, s[14:15]
	global_load_dwordx4 v[138:141], v202, s[12:13]
	global_load_dwordx4 v[142:145], v203, s[12:13]
	global_load_dwordx4 v[146:149], v204, s[12:13]
	global_load_dwordx4 v[150:153], v205, s[12:13]
	global_load_dwordx4 v[154:157], v206, s[12:13]
	global_load_dwordx4 v[158:161], v198, s[14:15] offset:64
	global_load_dwordx4 v[162:165], v199, s[14:15] offset:64
	global_load_dwordx4 v[166:169], v200, s[14:15] offset:64
	global_load_dwordx4 v[170:173], v201, s[14:15] offset:64
	global_load_dwordx4 v[174:177], v202, s[12:13] offset:64
	global_load_dwordx4 v[178:181], v203, s[12:13] offset:64
	global_load_dwordx4 v[182:185], v204, s[12:13] offset:64
	global_load_dwordx4 v[186:189], v205, s[12:13] offset:64
	global_load_dwordx4 v[190:193], v206, s[12:13] offset:64
	global_load_dwordx4 v[82:85], v198, s[14:15] offset:128
	global_load_dwordx4 v[86:89], v199, s[14:15] offset:128
	global_load_dwordx4 v[90:93], v200, s[14:15] offset:128
	global_load_dwordx4 v[94:97], v201, s[14:15] offset:128
	global_load_dwordx4 v[98:101], v202, s[12:13] offset:128
	global_load_dwordx4 v[102:105], v203, s[12:13] offset:128
	global_load_dwordx4 v[106:109], v204, s[12:13] offset:128
	global_load_dwordx4 v[110:113], v205, s[12:13] offset:128
	global_load_dwordx4 v[194:197], v206, s[12:13] offset:128
	s_waitcnt vmcnt(18)
	v_mfma_f32_16x16x32_bf16 v[2:5], v[138:141], v[122:125], v[2:5]
	v_mfma_f32_16x16x32_bf16 v[6:9], v[138:141], v[126:129], v[6:9]
	v_mfma_f32_16x16x32_bf16 v[10:13], v[138:141], v[130:133], v[10:13]
	v_mfma_f32_16x16x32_bf16 v[14:17], v[138:141], v[134:137], v[14:17]
	v_mfma_f32_16x16x32_bf16 v[18:21], v[142:145], v[122:125], v[18:21]
	v_mfma_f32_16x16x32_bf16 v[22:25], v[142:145], v[126:129], v[22:25]
	v_mfma_f32_16x16x32_bf16 v[26:29], v[142:145], v[130:133], v[26:29]
	v_mfma_f32_16x16x32_bf16 v[30:33], v[142:145], v[134:137], v[30:33]
	v_mfma_f32_16x16x32_bf16 v[34:37], v[146:149], v[122:125], v[34:37]
	v_mfma_f32_16x16x32_bf16 v[38:41], v[146:149], v[126:129], v[38:41]
	v_mfma_f32_16x16x32_bf16 v[42:45], v[146:149], v[130:133], v[42:45]
	v_mfma_f32_16x16x32_bf16 v[46:49], v[146:149], v[134:137], v[46:49]
	v_mfma_f32_16x16x32_bf16 v[50:53], v[150:153], v[122:125], v[50:53]
	v_mfma_f32_16x16x32_bf16 v[54:57], v[150:153], v[126:129], v[54:57]
	v_mfma_f32_16x16x32_bf16 v[58:61], v[150:153], v[130:133], v[58:61]
	v_mfma_f32_16x16x32_bf16 v[62:65], v[150:153], v[134:137], v[62:65]
	v_mfma_f32_16x16x32_bf16 v[66:69], v[154:157], v[122:125], v[66:69]
	v_mfma_f32_16x16x32_bf16 v[70:73], v[154:157], v[126:129], v[70:73]
	v_mfma_f32_16x16x32_bf16 v[74:77], v[154:157], v[130:133], v[74:77]
	v_mfma_f32_16x16x32_bf16 v[78:81], v[154:157], v[134:137], v[78:81]
	global_load_dwordx4 v[122:125], v198, s[14:15] offset:192
	global_load_dwordx4 v[126:129], v199, s[14:15] offset:192
	global_load_dwordx4 v[130:133], v200, s[14:15] offset:192
	global_load_dwordx4 v[134:137], v201, s[14:15] offset:192
	global_load_dwordx4 v[138:141], v202, s[12:13] offset:192
	global_load_dwordx4 v[142:145], v203, s[12:13] offset:192
	global_load_dwordx4 v[146:149], v204, s[12:13] offset:192
	global_load_dwordx4 v[150:153], v205, s[12:13] offset:192
	global_load_dwordx4 v[154:157], v206, s[12:13] offset:192
	s_waitcnt vmcnt(18)
	s_cmp_lt_u32 s8, 1
	s_cbranch_scc1 .Ls5s_sk1_0
	v_mfma_f32_16x16x32_bf16 v[2:5], v[174:177], v[158:161], v[2:5]
	v_mfma_f32_16x16x32_bf16 v[6:9], v[174:177], v[162:165], v[6:9]
	v_mfma_f32_16x16x32_bf16 v[10:13], v[174:177], v[166:169], v[10:13]
	v_mfma_f32_16x16x32_bf16 v[14:17], v[174:177], v[170:173], v[14:17]
.Ls5s_sk1_0:
	v_mfma_f32_16x16x32_bf16 v[18:21], v[178:181], v[158:161], v[18:21]
	v_mfma_f32_16x16x32_bf16 v[22:25], v[178:181], v[162:165], v[22:25]
	v_mfma_f32_16x16x32_bf16 v[26:29], v[178:181], v[166:169], v[26:29]
	v_mfma_f32_16x16x32_bf16 v[30:33], v[178:181], v[170:173], v[30:33]
	v_mfma_f32_16x16x32_bf16 v[34:37], v[182:185], v[158:161], v[34:37]
	v_mfma_f32_16x16x32_bf16 v[38:41], v[182:185], v[162:165], v[38:41]
	v_mfma_f32_16x16x32_bf16 v[42:45], v[182:185], v[166:169], v[42:45]
	v_mfma_f32_16x16x32_bf16 v[46:49], v[182:185], v[170:173], v[46:49]
	v_mfma_f32_16x16x32_bf16 v[50:53], v[186:189], v[158:161], v[50:53]
	v_mfma_f32_16x16x32_bf16 v[54:57], v[186:189], v[162:165], v[54:57]
	v_mfma_f32_16x16x32_bf16 v[58:61], v[186:189], v[166:169], v[58:61]
	v_mfma_f32_16x16x32_bf16 v[62:65], v[186:189], v[170:173], v[62:65]
	v_mfma_f32_16x16x32_bf16 v[66:69], v[190:193], v[158:161], v[66:69]
	v_mfma_f32_16x16x32_bf16 v[70:73], v[190:193], v[162:165], v[70:73]
	v_mfma_f32_16x16x32_bf16 v[74:77], v[190:193], v[166:169], v[74:77]
	v_mfma_f32_16x16x32_bf16 v[78:81], v[190:193], v[170:173], v[78:81]
	global_load_dwordx4 v[158:161], v198, s[14:15] offset:256
	global_load_dwordx4 v[162:165], v199, s[14:15] offset:256
	global_load_dwordx4 v[166:169], v200, s[14:15] offset:256
	global_load_dwordx4 v[170:173], v201, s[14:15] offset:256
	global_load_dwordx4 v[174:177], v202, s[12:13] offset:256
	global_load_dwordx4 v[178:181], v203, s[12:13] offset:256
	global_load_dwordx4 v[182:185], v204, s[12:13] offset:256
	global_load_dwordx4 v[186:189], v205, s[12:13] offset:256
	global_load_dwordx4 v[190:193], v206, s[12:13] offset:256
	s_waitcnt vmcnt(18)
	s_cmp_lt_u32 s8, 2
	s_cbranch_scc1 .Ls5s_sk2_0
	v_mfma_f32_16x16x32_bf16 v[2:5], v[98:101], v[82:85], v[2:5]
	v_mfma_f32_16x16x32_bf16 v[6:9], v[98:101], v[86:89], v[6:9]
	v_mfma_f32_16x16x32_bf16 v[10:13], v[98:101], v[90:93], v[10:13]
	v_mfma_f32_16x16x32_bf16 v[14:17], v[98:101], v[94:97], v[14:17]
; DEV void s5_task(int l, int b, int g, int wave, int lane, LAS unsigned char* sm, unsigned char* ws, float* out, const float* dskip) {
;     ...
;     for (int s = 0; s < 16; ++s) { const int k0 = 32 * s + 8 * fq;
;         bf16x8 bfr[4];
; #pragma unroll
;         for (int nt = 0; nt < 4; ++nt) bfr[nt] = *(const bf16x8*)(U + (size_t)(nt * 16 + fr) * 512 + k0);
; #pragma unroll
;         for (int i = 0; i < 4; ++i) { const int rt = wave + 8 * i;
;             if (2 * s <= rt) { const bf16x8 a = *(const bf16x8*)(TQ + (size_t)(rt * 16 + fr) * 512 + k0);
; #pragma unroll
;                 for (int nt = 0; nt < 4; ++nt) acc[i][nt] = __builtin_amdgcn_mfma_f32_16x16x32_bf16(a, bfr[nt], acc[i][nt], 0, 0, 0); } }
;         { const bf16x8 a = *(const bf16x8*)(TQ + (size_t)((32 + wave) * 16 + fr) * 512 + k0);
; #pragma unroll
;             for (int nt = 0; nt < 4; ++nt) acc[4][nt] = __builtin_amdgcn_mfma_f32_16x16x32_bf16(a, bfr[nt], acc[4][nt], 0, 0, 0); }
;     }
.Ls5s_sk2_0:
	v_mfma_f32_16x16x32_bf16 v[18:21], v[102:105], v[82:85], v[18:21]
	v_mfma_f32_16x16x32_bf16 v[22:25], v[102:105], v[86:89], v[22:25]
	v_mfma_f32_16x16x32_bf16 v[26:29], v[102:105], v[90:93], v[26:29]
	v_mfma_f32_16x16x32_bf16 v[30:33], v[102:105], v[94:97], v[30:33]
	v_mfma_f32_16x16x32_bf16 v[34:37], v[106:109], v[82:85], v[34:37]
	v_mfma_f32_16x16x32_bf16 v[38:41], v[106:109], v[86:89], v[38:41]
	v_mfma_f32_16x16x32_bf16 v[42:45], v[106:109], v[90:93], v[42:45]
	v_mfma_f32_16x16x32_bf16 v[46:49], v[106:109], v[94:97], v[46:49]
	v_mfma_f32_16x16x32_bf16 v[50:53], v[110:113], v[82:85], v[50:53]
	v_mfma_f32_16x16x32_bf16 v[54:57], v[110:113], v[86:89], v[54:57]
	v_mfma_f32_16x16x32_bf16 v[58:61], v[110:113], v[90:93], v[58:61]
	v_mfma_f32_16x16x32_bf16 v[62:65], v[110:113], v[94:97], v[62:65]
	v_mfma_f32_16x16x32_bf16 v[66:69], v[194:197], v[82:85], v[66:69]
	v_mfma_f32_16x16x32_bf16 v[70:73], v[194:197], v[86:89], v[70:73]
	v_mfma_f32_16x16x32_bf16 v[74:77], v[194:197], v[90:93], v[74:77]
	v_mfma_f32_16x16x32_bf16 v[78:81], v[194:197], v[94:97], v[78:81]
	global_load_dwordx4 v[82:85], v198, s[14:15] offset:320
	global_load_dwordx4 v[86:89], v199, s[14:15] offset:320
	global_load_dwordx4 v[90:93], v200, s[14:15] offset:320
	global_load_dwordx4 v[94:97], v201, s[14:15] offset:320
	global_load_dwordx4 v[98:101], v202, s[12:13] offset:320
	global_load_dwordx4 v[102:105], v203, s[12:13] offset:320
	global_load_dwordx4 v[106:109], v204, s[12:13] offset:320
	global_load_dwordx4 v[110:113], v205, s[12:13] offset:320
	global_load_dwordx4 v[194:197], v206, s[12:13] offset:320
	s_waitcnt vmcnt(18)
	s_cmp_lt_u32 s8, 3
	s_cbranch_scc1 .Ls5s_sk3_0
	v_mfma_f32_16x16x32_bf16 v[2:5], v[138:141], v[122:125], v[2:5]
	v_mfma_f32_16x16x32_bf16 v[6:9], v[138:141], v[126:129], v[6:9]
	v_mfma_f32_16x16x32_bf16 v[10:13], v[138:141], v[130:133], v[10:13]
	v_mfma_f32_16x16x32_bf16 v[14:17], v[138:141], v[134:137], v[14:17]
.Ls5s_sk3_0:
	v_mfma_f32_16x16x32_bf16 v[18:21], v[142:145], v[122:125], v[18:21]
	v_mfma_f32_16x16x32_bf16 v[22:25], v[142:145], v[126:129], v[22:25]
	v_mfma_f32_16x16x32_bf16 v[26:29], v[142:145], v[130:133], v[26:29]
	v_mfma_f32_16x16x32_bf16 v[30:33], v[142:145], v[134:137], v[30:33]
	v_mfma_f32_16x16x32_bf16 v[34:37], v[146:149], v[122:125], v[34:37]
	v_mfma_f32_16x16x32_bf16 v[38:41], v[146:149], v[126:129], v[38:41]
	v_mfma_f32_16x16x32_bf16 v[42:45], v[146:149], v[130:133], v[42:45]
	v_mfma_f32_16x16x32_bf16 v[46:49], v[146:149], v[134:137], v[46:49]
	v_mfma_f32_16x16x32_bf16 v[50:53], v[150:153], v[122:125], v[50:53]
	v_mfma_f32_16x16x32_bf16 v[54:57], v[150:153], v[126:129], v[54:57]
	v_mfma_f32_16x16x32_bf16 v[58:61], v[150:153], v[130:133], v[58:61]
	v_mfma_f32_16x16x32_bf16 v[62:65], v[150:153], v[134:137], v[62:65]
	v_mfma_f32_16x16x32_bf16 v[66:69], v[154:157], v[122:125], v[66:69]
	v_mfma_f32_16x16x32_bf16 v[70:73], v[154:157], v[126:129], v[70:73]
	v_mfma_f32_16x16x32_bf16 v[74:77], v[154:157], v[130:133], v[74:77]
	v_mfma_f32_16x16x32_bf16 v[78:81], v[154:157], v[134:137], v[78:81]
	global_load_dwordx4 v[122:125], v198, s[14:15] offset:384
	global_load_dwordx4 v[126:129], v199, s[14:15] offset:384
	global_load_dwordx4 v[130:133], v200, s[14:15] offset:384
	global_load_dwordx4 v[134:137], v201, s[14:15] offset:384
	global_load_dwordx4 v[138:141], v202, s[12:13] offset:384
	global_load_dwordx4 v[142:145], v203, s[12:13] offset:384
	global_load_dwordx4 v[146:149], v204, s[12:13] offset:384
	global_load_dwordx4 v[150:153], v205, s[12:13] offset:384
	global_load_dwordx4 v[154:157], v206, s[12:13] offset:384
	s_waitcnt vmcnt(18)
	v_mfma_f32_16x16x32_bf16 v[18:21], v[178:181], v[158:161], v[18:21]
	v_mfma_f32_16x16x32_bf16 v[22:25], v[178:181], v[162:165], v[22:25]
	v_mfma_f32_16x16x32_bf16 v[26:29], v[178:181], v[166:169], v[26:29]
	v_mfma_f32_16x16x32_bf16 v[30:33], v[178:181], v[170:173], v[30:33]
	v_mfma_f32_16x16x32_bf16 v[34:37], v[182:185], v[158:161], v[34:37]
	v_mfma_f32_16x16x32_bf16 v[38:41], v[182:185], v[162:165], v[38:41]
	v_mfma_f32_16x16x32_bf16 v[42:45], v[182:185], v[166:169], v[42:45]
	v_mfma_f32_16x16x32_bf16 v[46:49], v[182:185], v[170:173], v[46:49]
	v_mfma_f32_16x16x32_bf16 v[50:53], v[186:189], v[158:161], v[50:53]
	v_mfma_f32_16x16x32_bf16 v[54:57], v[186:189], v[162:165], v[54:57]
	v_mfma_f32_16x16x32_bf16 v[58:61], v[186:189], v[166:169], v[58:61]
	v_mfma_f32_16x16x32_bf16 v[62:65], v[186:189], v[170:173], v[62:65]
	v_mfma_f32_16x16x32_bf16 v[66:69], v[190:193], v[158:161], v[66:69]
	v_mfma_f32_16x16x32_bf16 v[70:73], v[190:193], v[162:165], v[70:73]
	v_mfma_f32_16x16x32_bf16 v[74:77], v[190:193], v[166:169], v[74:77]
	v_mfma_f32_16x16x32_bf16 v[78:81], v[190:193], v[170:173], v[78:81]
	global_load_dwordx4 v[158:161], v198, s[14:15] offset:448
	global_load_dwordx4 v[162:165], v199, s[14:15] offset:448
	global_load_dwordx4 v[166:169], v200, s[14:15] offset:448
	global_load_dwordx4 v[170:173], v201, s[14:15] offset:448
	global_load_dwordx4 v[174:177], v202, s[12:13] offset:448
	global_load_dwordx4 v[178:181], v203, s[12:13] offset:448
	global_load_dwordx4 v[182:185], v204, s[12:13] offset:448
	global_load_dwordx4 v[186:189], v205, s[12:13] offset:448
	global_load_dwordx4 v[190:193], v206, s[12:13] offset:448
	s_waitcnt vmcnt(18)
	s_cmp_lt_u32 s9, 5
	s_cbranch_scc1 .Ls5s_sk5_1
	v_mfma_f32_16x16x32_bf16 v[18:21], v[102:105], v[82:85], v[18:21]
	v_mfma_f32_16x16x32_bf16 v[22:25], v[102:105], v[86:89], v[22:25]
	v_mfma_f32_16x16x32_bf16 v[26:29], v[102:105], v[90:93], v[26:29]
	v_mfma_f32_16x16x32_bf16 v[30:33], v[102:105], v[94:97], v[30:33]
; DEV void s5_task(int l, int b, int g, int wave, int lane, LAS unsigned char* sm, unsigned char* ws, float* out, const float* dskip) {
;     ...
;     for (int s = 0; s < 16; ++s) { const int k0 = 32 * s + 8 * fq;
;         bf16x8 bfr[4];
; #pragma unroll
;         for (int nt = 0; nt < 4; ++nt) bfr[nt] = *(const bf16x8*)(U + (size_t)(nt * 16 + fr) * 512 + k0);
; #pragma unroll
;         for (int i = 0; i < 4; ++i) { const int rt = wave + 8 * i;
;             if (2 * s <= rt) { const bf16x8 a = *(const bf16x8*)(TQ + (size_t)(rt * 16 + fr) * 512 + k0);
; #pragma unroll
;                 for (int nt = 0; nt < 4; ++nt) acc[i][nt] = __builtin_amdgcn_mfma_f32_16x16x32_bf16(a, bfr[nt], acc[i][nt], 0, 0, 0); } }
;         { const bf16x8 a = *(const bf16x8*)(TQ + (size_t)((32 + wave) * 16 + fr) * 512 + k0);
; #pragma unroll
;             for (int nt = 0; nt < 4; ++nt) acc[4][nt] = __builtin_amdgcn_mfma_f32_16x16x32_bf16(a, bfr[nt], acc[4][nt], 0, 0, 0); }
;     }
.Ls5s_sk5_1:
	v_mfma_f32_16x16x32_bf16 v[34:37], v[106:109], v[82:85], v[34:37]
	v_mfma_f32_16x16x32_bf16 v[38:41], v[106:109], v[86:89], v[38:41]
	v_mfma_f32_16x16x32_bf16 v[42:45], v[106:109], v[90:93], v[42:45]
	v_mfma_f32_16x16x32_bf16 v[46:49], v[106:109], v[94:97], v[46:49]
	v_mfma_f32_16x16x32_bf16 v[50:53], v[110:113], v[82:85], v[50:53]
	v_mfma_f32_16x16x32_bf16 v[54:57], v[110:113], v[86:89], v[54:57]
	v_mfma_f32_16x16x32_bf16 v[58:61], v[110:113], v[90:93], v[58:61]
	v_mfma_f32_16x16x32_bf16 v[62:65], v[110:113], v[94:97], v[62:65]
	v_mfma_f32_16x16x32_bf16 v[66:69], v[194:197], v[82:85], v[66:69]
	v_mfma_f32_16x16x32_bf16 v[70:73], v[194:197], v[86:89], v[70:73]
	v_mfma_f32_16x16x32_bf16 v[74:77], v[194:197], v[90:93], v[74:77]
	v_mfma_f32_16x16x32_bf16 v[78:81], v[194:197], v[94:97], v[78:81]
	global_load_dwordx4 v[82:85], v198, s[14:15] offset:512
	global_load_dwordx4 v[86:89], v199, s[14:15] offset:512
	global_load_dwordx4 v[90:93], v200, s[14:15] offset:512
	global_load_dwordx4 v[94:97], v201, s[14:15] offset:512
	global_load_dwordx4 v[98:101], v202, s[12:13] offset:512
	global_load_dwordx4 v[102:105], v203, s[12:13] offset:512
	global_load_dwordx4 v[106:109], v204, s[12:13] offset:512
	global_load_dwordx4 v[110:113], v205, s[12:13] offset:512
	global_load_dwordx4 v[194:197], v206, s[12:13] offset:512
	s_waitcnt vmcnt(18)
	s_cmp_lt_u32 s9, 6
	s_cbranch_scc1 .Ls5s_sk6_1
	v_mfma_f32_16x16x32_bf16 v[18:21], v[142:145], v[122:125], v[18:21]
	v_mfma_f32_16x16x32_bf16 v[22:25], v[142:145], v[126:129], v[22:25]
	v_mfma_f32_16x16x32_bf16 v[26:29], v[142:145], v[130:133], v[26:29]
	v_mfma_f32_16x16x32_bf16 v[30:33], v[142:145], v[134:137], v[30:33]
.Ls5s_sk6_1:
	v_mfma_f32_16x16x32_bf16 v[34:37], v[146:149], v[122:125], v[34:37]
	v_mfma_f32_16x16x32_bf16 v[38:41], v[146:149], v[126:129], v[38:41]
	v_mfma_f32_16x16x32_bf16 v[42:45], v[146:149], v[130:133], v[42:45]
	v_mfma_f32_16x16x32_bf16 v[46:49], v[146:149], v[134:137], v[46:49]
	v_mfma_f32_16x16x32_bf16 v[50:53], v[150:153], v[122:125], v[50:53]
	v_mfma_f32_16x16x32_bf16 v[54:57], v[150:153], v[126:129], v[54:57]
	v_mfma_f32_16x16x32_bf16 v[58:61], v[150:153], v[130:133], v[58:61]
	v_mfma_f32_16x16x32_bf16 v[62:65], v[150:153], v[134:137], v[62:65]
	v_mfma_f32_16x16x32_bf16 v[66:69], v[154:157], v[122:125], v[66:69]
	v_mfma_f32_16x16x32_bf16 v[70:73], v[154:157], v[126:129], v[70:73]
	v_mfma_f32_16x16x32_bf16 v[74:77], v[154:157], v[130:133], v[74:77]
	v_mfma_f32_16x16x32_bf16 v[78:81], v[154:157], v[134:137], v[78:81]
	global_load_dwordx4 v[122:125], v198, s[14:15] offset:576
	global_load_dwordx4 v[126:129], v199, s[14:15] offset:576
	global_load_dwordx4 v[130:133], v200, s[14:15] offset:576
	global_load_dwordx4 v[134:137], v201, s[14:15] offset:576
	global_load_dwordx4 v[138:141], v202, s[12:13] offset:576
	global_load_dwordx4 v[142:145], v203, s[12:13] offset:576
	global_load_dwordx4 v[146:149], v204, s[12:13] offset:576
	global_load_dwordx4 v[150:153], v205, s[12:13] offset:576
	global_load_dwordx4 v[154:157], v206, s[12:13] offset:576
	s_waitcnt vmcnt(18)
	s_cmp_lt_u32 s9, 7
	s_cbranch_scc1 .Ls5s_sk7_1
	v_mfma_f32_16x16x32_bf16 v[18:21], v[178:181], v[158:161], v[18:21]
	v_mfma_f32_16x16x32_bf16 v[22:25], v[178:181], v[162:165], v[22:25]
	v_mfma_f32_16x16x32_bf16 v[26:29], v[178:181], v[166:169], v[26:29]
	v_mfma_f32_16x16x32_bf16 v[30:33], v[178:181], v[170:173], v[30:33]
.Ls5s_sk7_1:
	v_mfma_f32_16x16x32_bf16 v[34:37], v[182:185], v[158:161], v[34:37]
	v_mfma_f32_16x16x32_bf16 v[38:41], v[182:185], v[162:165], v[38:41]
	v_mfma_f32_16x16x32_bf16 v[42:45], v[182:185], v[166:169], v[42:45]
	v_mfma_f32_16x16x32_bf16 v[46:49], v[182:185], v[170:173], v[46:49]
	v_mfma_f32_16x16x32_bf16 v[50:53], v[186:189], v[158:161], v[50:53]
	v_mfma_f32_16x16x32_bf16 v[54:57], v[186:189], v[162:165], v[54:57]
	v_mfma_f32_16x16x32_bf16 v[58:61], v[186:189], v[166:169], v[58:61]
	v_mfma_f32_16x16x32_bf16 v[62:65], v[186:189], v[170:173], v[62:65]
	v_mfma_f32_16x16x32_bf16 v[66:69], v[190:193], v[158:161], v[66:69]
	v_mfma_f32_16x16x32_bf16 v[70:73], v[190:193], v[162:165], v[70:73]
	v_mfma_f32_16x16x32_bf16 v[74:77], v[190:193], v[166:169], v[74:77]
	v_mfma_f32_16x16x32_bf16 v[78:81], v[190:193], v[170:173], v[78:81]
	global_load_dwordx4 v[158:161], v198, s[14:15] offset:640
	global_load_dwordx4 v[162:165], v199, s[14:15] offset:640
	global_load_dwordx4 v[166:169], v200, s[14:15] offset:640
	global_load_dwordx4 v[170:173], v201, s[14:15] offset:640
	global_load_dwordx4 v[174:177], v202, s[12:13] offset:640
	global_load_dwordx4 v[178:181], v203, s[12:13] offset:640
	global_load_dwordx4 v[182:185], v204, s[12:13] offset:640
	global_load_dwordx4 v[186:189], v205, s[12:13] offset:640
	global_load_dwordx4 v[190:193], v206, s[12:13] offset:640
	s_waitcnt vmcnt(18)
	v_mfma_f32_16x16x32_bf16 v[34:37], v[106:109], v[82:85], v[34:37]
	v_mfma_f32_16x16x32_bf16 v[38:41], v[106:109], v[86:89], v[38:41]
	v_mfma_f32_16x16x32_bf16 v[42:45], v[106:109], v[90:93], v[42:45]
	v_mfma_f32_16x16x32_bf16 v[46:49], v[106:109], v[94:97], v[46:49]
	v_mfma_f32_16x16x32_bf16 v[50:53], v[110:113], v[82:85], v[50:53]
	v_mfma_f32_16x16x32_bf16 v[54:57], v[110:113], v[86:89], v[54:57]
	v_mfma_f32_16x16x32_bf16 v[58:61], v[110:113], v[90:93], v[58:61]
	v_mfma_f32_16x16x32_bf16 v[62:65], v[110:113], v[94:97], v[62:65]
	v_mfma_f32_16x16x32_bf16 v[66:69], v[194:197], v[82:85], v[66:69]
	v_mfma_f32_16x16x32_bf16 v[70:73], v[194:197], v[86:89], v[70:73]
	v_mfma_f32_16x16x32_bf16 v[74:77], v[194:197], v[90:93], v[74:77]
	v_mfma_f32_16x16x32_bf16 v[78:81], v[194:197], v[94:97], v[78:81]
	global_load_dwordx4 v[82:85], v198, s[14:15] offset:704
	global_load_dwordx4 v[86:89], v199, s[14:15] offset:704
	global_load_dwordx4 v[90:93], v200, s[14:15] offset:704
	global_load_dwordx4 v[94:97], v201, s[14:15] offset:704
	global_load_dwordx4 v[98:101], v202, s[12:13] offset:704
	global_load_dwordx4 v[102:105], v203, s[12:13] offset:704
	global_load_dwordx4 v[106:109], v204, s[12:13] offset:704
	global_load_dwordx4 v[110:113], v205, s[12:13] offset:704
	global_load_dwordx4 v[194:197], v206, s[12:13] offset:704
	s_waitcnt vmcnt(18)
	s_cmp_lt_u32 s10, 9
	s_cbranch_scc1 .Ls5s_sk9_2
	v_mfma_f32_16x16x32_bf16 v[34:37], v[146:149], v[122:125], v[34:37]
	v_mfma_f32_16x16x32_bf16 v[38:41], v[146:149], v[126:129], v[38:41]
	v_mfma_f32_16x16x32_bf16 v[42:45], v[146:149], v[130:133], v[42:45]
	v_mfma_f32_16x16x32_bf16 v[46:49], v[146:149], v[134:137], v[46:49]
; DEV void s5_task(int l, int b, int g, int wave, int lane, LAS unsigned char* sm, unsigned char* ws, float* out, const float* dskip) {
;     ...
;     for (int s = 0; s < 16; ++s) { const int k0 = 32 * s + 8 * fq;
;         bf16x8 bfr[4];
; #pragma unroll
;         for (int nt = 0; nt < 4; ++nt) bfr[nt] = *(const bf16x8*)(U + (size_t)(nt * 16 + fr) * 512 + k0);
; #pragma unroll
;         for (int i = 0; i < 4; ++i) { const int rt = wave + 8 * i;
;             if (2 * s <= rt) { const bf16x8 a = *(const bf16x8*)(TQ + (size_t)(rt * 16 + fr) * 512 + k0);
; #pragma unroll
;                 for (int nt = 0; nt < 4; ++nt) acc[i][nt] = __builtin_amdgcn_mfma_f32_16x16x32_bf16(a, bfr[nt], acc[i][nt], 0, 0, 0); } }
;         { const bf16x8 a = *(const bf16x8*)(TQ + (size_t)((32 + wave) * 16 + fr) * 512 + k0);
; #pragma unroll
;             for (int nt = 0; nt < 4; ++nt) acc[4][nt] = __builtin_amdgcn_mfma_f32_16x16x32_bf16(a, bfr[nt], acc[4][nt], 0, 0, 0); }
;     }
.Ls5s_sk9_2:
	v_mfma_f32_16x16x32_bf16 v[50:53], v[150:153], v[122:125], v[50:53]
	v_mfma_f32_16x16x32_bf16 v[54:57], v[150:153], v[126:129], v[54:57]
	v_mfma_f32_16x16x32_bf16 v[58:61], v[150:153], v[130:133], v[58:61]
	v_mfma_f32_16x16x32_bf16 v[62:65], v[150:153], v[134:137], v[62:65]
	v_mfma_f32_16x16x32_bf16 v[66:69], v[154:157], v[122:125], v[66:69]
	v_mfma_f32_16x16x32_bf16 v[70:73], v[154:157], v[126:129], v[70:73]
	v_mfma_f32_16x16x32_bf16 v[74:77], v[154:157], v[130:133], v[74:77]
	v_mfma_f32_16x16x32_bf16 v[78:81], v[154:157], v[134:137], v[78:81]
	global_load_dwordx4 v[122:125], v198, s[14:15] offset:768
	global_load_dwordx4 v[126:129], v199, s[14:15] offset:768
	global_load_dwordx4 v[130:133], v200, s[14:15] offset:768
	global_load_dwordx4 v[134:137], v201, s[14:15] offset:768
	global_load_dwordx4 v[138:141], v202, s[12:13] offset:768
	global_load_dwordx4 v[142:145], v203, s[12:13] offset:768
	global_load_dwordx4 v[146:149], v204, s[12:13] offset:768
	global_load_dwordx4 v[150:153], v205, s[12:13] offset:768
	global_load_dwordx4 v[154:157], v206, s[12:13] offset:768
	s_waitcnt vmcnt(18)
	s_cmp_lt_u32 s10, 10
	s_cbranch_scc1 .Ls5s_sk10_2
	v_mfma_f32_16x16x32_bf16 v[34:37], v[182:185], v[158:161], v[34:37]
	v_mfma_f32_16x16x32_bf16 v[38:41], v[182:185], v[162:165], v[38:41]
	v_mfma_f32_16x16x32_bf16 v[42:45], v[182:185], v[166:169], v[42:45]
	v_mfma_f32_16x16x32_bf16 v[46:49], v[182:185], v[170:173], v[46:49]
.Ls5s_sk10_2:
	v_mfma_f32_16x16x32_bf16 v[50:53], v[186:189], v[158:161], v[50:53]
	v_mfma_f32_16x16x32_bf16 v[54:57], v[186:189], v[162:165], v[54:57]
	v_mfma_f32_16x16x32_bf16 v[58:61], v[186:189], v[166:169], v[58:61]
	v_mfma_f32_16x16x32_bf16 v[62:65], v[186:189], v[170:173], v[62:65]
	v_mfma_f32_16x16x32_bf16 v[66:69], v[190:193], v[158:161], v[66:69]
	v_mfma_f32_16x16x32_bf16 v[70:73], v[190:193], v[162:165], v[70:73]
	v_mfma_f32_16x16x32_bf16 v[74:77], v[190:193], v[166:169], v[74:77]
	v_mfma_f32_16x16x32_bf16 v[78:81], v[190:193], v[170:173], v[78:81]
	global_load_dwordx4 v[158:161], v198, s[14:15] offset:832
	global_load_dwordx4 v[162:165], v199, s[14:15] offset:832
	global_load_dwordx4 v[166:169], v200, s[14:15] offset:832
	global_load_dwordx4 v[170:173], v201, s[14:15] offset:832
	global_load_dwordx4 v[174:177], v202, s[12:13] offset:832
	global_load_dwordx4 v[178:181], v203, s[12:13] offset:832
	global_load_dwordx4 v[182:185], v204, s[12:13] offset:832
	global_load_dwordx4 v[186:189], v205, s[12:13] offset:832
	global_load_dwordx4 v[190:193], v206, s[12:13] offset:832
	s_waitcnt vmcnt(18)
	s_cmp_lt_u32 s10, 11
	s_cbranch_scc1 .Ls5s_sk11_2
	v_mfma_f32_16x16x32_bf16 v[34:37], v[106:109], v[82:85], v[34:37]
	v_mfma_f32_16x16x32_bf16 v[38:41], v[106:109], v[86:89], v[38:41]
	v_mfma_f32_16x16x32_bf16 v[42:45], v[106:109], v[90:93], v[42:45]
	v_mfma_f32_16x16x32_bf16 v[46:49], v[106:109], v[94:97], v[46:49]
.Ls5s_sk11_2:
	v_mfma_f32_16x16x32_bf16 v[50:53], v[110:113], v[82:85], v[50:53]
	v_mfma_f32_16x16x32_bf16 v[54:57], v[110:113], v[86:89], v[54:57]
	v_mfma_f32_16x16x32_bf16 v[58:61], v[110:113], v[90:93], v[58:61]
	v_mfma_f32_16x16x32_bf16 v[62:65], v[110:113], v[94:97], v[62:65]
	v_mfma_f32_16x16x32_bf16 v[66:69], v[194:197], v[82:85], v[66:69]
	v_mfma_f32_16x16x32_bf16 v[70:73], v[194:197], v[86:89], v[70:73]
	v_mfma_f32_16x16x32_bf16 v[74:77], v[194:197], v[90:93], v[74:77]
	v_mfma_f32_16x16x32_bf16 v[78:81], v[194:197], v[94:97], v[78:81]
	global_load_dwordx4 v[82:85], v198, s[14:15] offset:896
	global_load_dwordx4 v[86:89], v199, s[14:15] offset:896
	global_load_dwordx4 v[90:93], v200, s[14:15] offset:896
	global_load_dwordx4 v[94:97], v201, s[14:15] offset:896
	global_load_dwordx4 v[98:101], v202, s[12:13] offset:896
	global_load_dwordx4 v[102:105], v203, s[12:13] offset:896
	global_load_dwordx4 v[106:109], v204, s[12:13] offset:896
	global_load_dwordx4 v[110:113], v205, s[12:13] offset:896
	global_load_dwordx4 v[194:197], v206, s[12:13] offset:896
	s_waitcnt vmcnt(18)
	v_mfma_f32_16x16x32_bf16 v[50:53], v[150:153], v[122:125], v[50:53]
	v_mfma_f32_16x16x32_bf16 v[54:57], v[150:153], v[126:129], v[54:57]
	v_mfma_f32_16x16x32_bf16 v[58:61], v[150:153], v[130:133], v[58:61]
	v_mfma_f32_16x16x32_bf16 v[62:65], v[150:153], v[134:137], v[62:65]
	v_mfma_f32_16x16x32_bf16 v[66:69], v[154:157], v[122:125], v[66:69]
	v_mfma_f32_16x16x32_bf16 v[70:73], v[154:157], v[126:129], v[70:73]
	v_mfma_f32_16x16x32_bf16 v[74:77], v[154:157], v[130:133], v[74:77]
	v_mfma_f32_16x16x32_bf16 v[78:81], v[154:157], v[134:137], v[78:81]
	global_load_dwordx4 v[122:125], v198, s[14:15] offset:960
	global_load_dwordx4 v[126:129], v199, s[14:15] offset:960
	global_load_dwordx4 v[130:133], v200, s[14:15] offset:960
	global_load_dwordx4 v[134:137], v201, s[14:15] offset:960
	global_load_dwordx4 v[138:141], v202, s[12:13] offset:960
	global_load_dwordx4 v[142:145], v203, s[12:13] offset:960
	global_load_dwordx4 v[146:149], v204, s[12:13] offset:960
	global_load_dwordx4 v[150:153], v205, s[12:13] offset:960
	global_load_dwordx4 v[154:157], v206, s[12:13] offset:960
	s_waitcnt vmcnt(18)
	s_cmp_lt_u32 s11, 13
	s_cbranch_scc1 .Ls5s_sk13_3
	v_mfma_f32_16x16x32_bf16 v[50:53], v[186:189], v[158:161], v[50:53]
	v_mfma_f32_16x16x32_bf16 v[54:57], v[186:189], v[162:165], v[54:57]
	v_mfma_f32_16x16x32_bf16 v[58:61], v[186:189], v[166:169], v[58:61]
	v_mfma_f32_16x16x32_bf16 v[62:65], v[186:189], v[170:173], v[62:65]
; DEV bf16_t f2bf(float f) { unsigned u = __float_as_uint(f); u += 0x7fffu + ((u >> 16) & 1u); return (bf16_t)(u >> 16); }
; #define LAS __attribute__((address_space(3)))
; DEV void s5_task(int l, int b, int g, int wave, int lane, LAS unsigned char* sm, unsigned char* ws, float* out, const float* dskip) {
;     ...
;         { const bf16x8 a = *(const bf16x8*)(TQ + (size_t)((32 + wave) * 16 + fr) * 512 + k0);
; #pragma unroll
;             for (int nt = 0; nt < 4; ++nt) acc[4][nt] = __builtin_amdgcn_mfma_f32_16x16x32_bf16(a, bfr[nt], acc[4][nt], 0, 0, 0); }
;     }
; #pragma unroll
;     for (int nt = 0; nt < 4; ++nt) *(LAS f32x4*)(Hloc + (nt * 16 + fr) * 128 + 16 * wave + 4 * fq) = acc[4][nt];
;     __syncthreads();
;     if (wave == 0) { const float2 aL = ((const float2*)(ws + WS_S5 + (size_t)lg * S5_SIZE + S5_AL))[lane]; float hr = 0.f, hi = 0.f;
;         for (int n = 0; n < 64; ++n) { Hin[n * 128 + lane] = f2bf(hr); Hin[n * 128 + 64 + lane] = f2bf(hi);
;             const float lr = Hloc[n * 128 + lane], li = Hloc[n * 128 + 64 + lane];
;             const float nr = aL.x * hr - aL.y * hi + lr, ni = aL.x * hi + aL.y * hr + li; hr = nr; hi = ni; }
.Ls5s_sk13_3:
	v_mfma_f32_16x16x32_bf16 v[66:69], v[190:193], v[158:161], v[66:69]
	v_mfma_f32_16x16x32_bf16 v[70:73], v[190:193], v[162:165], v[70:73]
	v_mfma_f32_16x16x32_bf16 v[74:77], v[190:193], v[166:169], v[74:77]
	v_mfma_f32_16x16x32_bf16 v[78:81], v[190:193], v[170:173], v[78:81]
	s_waitcnt vmcnt(9)
	s_cmp_lt_u32 s11, 14
	s_cbranch_scc1 .Ls5s_sk14_3
	v_mfma_f32_16x16x32_bf16 v[50:53], v[110:113], v[82:85], v[50:53]
	v_mfma_f32_16x16x32_bf16 v[54:57], v[110:113], v[86:89], v[54:57]
	v_mfma_f32_16x16x32_bf16 v[58:61], v[110:113], v[90:93], v[58:61]
	v_mfma_f32_16x16x32_bf16 v[62:65], v[110:113], v[94:97], v[62:65]
.Ls5s_sk14_3:
	v_mfma_f32_16x16x32_bf16 v[66:69], v[194:197], v[82:85], v[66:69]
	v_mfma_f32_16x16x32_bf16 v[70:73], v[194:197], v[86:89], v[70:73]
	v_mfma_f32_16x16x32_bf16 v[74:77], v[194:197], v[90:93], v[74:77]
	v_mfma_f32_16x16x32_bf16 v[78:81], v[194:197], v[94:97], v[78:81]
	s_waitcnt vmcnt(0)
	s_cmp_lt_u32 s11, 15
	s_cbranch_scc1 .Ls5s_sk15_3
	v_mfma_f32_16x16x32_bf16 v[50:53], v[150:153], v[122:125], v[50:53]
	v_mfma_f32_16x16x32_bf16 v[54:57], v[150:153], v[126:129], v[54:57]
	v_mfma_f32_16x16x32_bf16 v[58:61], v[150:153], v[130:133], v[58:61]
	v_mfma_f32_16x16x32_bf16 v[62:65], v[150:153], v[134:137], v[62:65]
.Ls5s_sk15_3:
	v_mfma_f32_16x16x32_bf16 v[66:69], v[154:157], v[122:125], v[66:69]
	v_mfma_f32_16x16x32_bf16 v[70:73], v[154:157], v[126:129], v[70:73]
	v_mfma_f32_16x16x32_bf16 v[74:77], v[154:157], v[130:133], v[74:77]
	v_mfma_f32_16x16x32_bf16 v[78:81], v[154:157], v[134:137], v[78:81]
	s_sub_u32 s6, s12, 0x200
	s_subb_u32 s7, s13, 0
	s_cmp_lg_u32 s4, 0
	s_cbranch_scc1 .Ls5s_noal
	v_lshlrev_b32_e32 v220, 3, v116
	global_load_dwordx2 v[226:227], v220, s[6:7]
.Ls5s_noal:
	global_load_dwordx4 v[122:125], v207, s[18:19]
	global_load_dwordx4 v[126:129], v208, s[18:19]
	global_load_dwordx4 v[130:133], v209, s[18:19]
	global_load_dwordx4 v[134:137], v210, s[18:19]
	global_load_dwordx4 v[138:141], v207, s[18:19] offset:64
	global_load_dwordx4 v[142:145], v208, s[18:19] offset:64
	global_load_dwordx4 v[146:149], v209, s[18:19] offset:64
	global_load_dwordx4 v[150:153], v210, s[18:19] offset:64
	global_load_dwordx4 v[154:157], v207, s[18:19] offset:128
	global_load_dwordx4 v[158:161], v208, s[18:19] offset:128
	global_load_dwordx4 v[162:165], v209, s[18:19] offset:128
	global_load_dwordx4 v[166:169], v210, s[18:19] offset:128
	global_load_dwordx4 v[170:173], v207, s[18:19] offset:192
	global_load_dwordx4 v[174:177], v208, s[18:19] offset:192
	global_load_dwordx4 v[178:181], v209, s[18:19] offset:192
	global_load_dwordx4 v[182:185], v210, s[18:19] offset:192
	global_load_dwordx2 v[82:83], v211, s[14:15]
	global_load_dwordx2 v[84:85], v212, s[14:15]
	global_load_dwordx2 v[86:87], v213, s[14:15]
	global_load_dwordx2 v[88:89], v214, s[14:15]
	global_load_dwordx2 v[90:91], v211, s[14:15] offset:256
	global_load_dwordx2 v[92:93], v212, s[14:15] offset:256
	global_load_dwordx2 v[94:95], v213, s[14:15] offset:256
	global_load_dwordx2 v[96:97], v214, s[14:15] offset:256
	global_load_dwordx2 v[98:99], v211, s[14:15] offset:512
	global_load_dwordx2 v[100:101], v212, s[14:15] offset:512
	global_load_dwordx2 v[102:103], v213, s[14:15] offset:512
	global_load_dwordx2 v[104:105], v214, s[14:15] offset:512
	global_load_dwordx2 v[106:107], v211, s[14:15] offset:768
	global_load_dwordx2 v[108:109], v212, s[14:15] offset:768
	global_load_dwordx2 v[110:111], v213, s[14:15] offset:768
	global_load_dwordx2 v[112:113], v214, s[14:15] offset:768
	s_lshl_b32 s3, s1, 6
	s_add_u32 s6, s16, s3
	s_addc_u32 s7, s17, 0
	v_lshrrev_b32_e32 v0, 4, v116
	v_lshlrev_b32_e32 v0, 4, v0
	global_load_dwordx4 v[222:225], v0, s[6:7]
	ds_write_b128 v215, v[66:69]
	ds_write_b128 v215, v[70:73] offset:8192
	ds_write_b128 v215, v[74:77] offset:16384
	ds_write_b128 v215, v[78:81] offset:24576
	s_waitcnt lgkmcnt(0)
	s_barrier
	s_cmp_lg_u32 s4, 0
	s_cbranch_scc1 .Ls5s_noscan
	ds_read2st64_b32 v[230:231], v217 offset0:0 offset1:1
	ds_read2st64_b32 v[232:233], v217 offset0:2 offset1:3
	ds_read2st64_b32 v[234:235], v217 offset0:4 offset1:5
	ds_read2st64_b32 v[238:239], v217 offset0:6 offset1:7
	v_mov_b32_e32 v228, 0
	v_mov_b32_e32 v229, 0
	s_waitcnt vmcnt(33)
	v_cvt_pk_bf16_f32 v220, v228, v229
	v_mul_f32_e32 v237, v227, v229
	v_mul_f32_e32 v247, v227, v228
	ds_write_b16 v216, v220 offset:0
	ds_write_b16_d16_hi v216, v220 offset:128
	v_fma_f32 v228, v226, v228, -v237
	v_fma_f32 v229, v226, v229, v247
	s_waitcnt lgkmcnt(5)
	v_add_f32_e32 v228, v228, v230
	v_add_f32_e32 v229, v229, v231
	ds_read2st64_b32 v[230:231], v217 offset0:8 offset1:9
	v_cvt_pk_bf16_f32 v220, v228, v229
	v_mul_f32_e32 v237, v227, v229
	v_mul_f32_e32 v247, v227, v228
	ds_write_b16 v216, v220 offset:256
	ds_write_b16_d16_hi v216, v220 offset:384
	v_fma_f32 v228, v226, v228, -v237
	v_fma_f32 v229, v226, v229, v247
	s_waitcnt lgkmcnt(7)
	v_add_f32_e32 v228, v228, v232
	v_add_f32_e32 v229, v229, v233
	ds_read2st64_b32 v[232:233], v217 offset0:10 offset1:11
	v_cvt_pk_bf16_f32 v220, v228, v229
	v_mul_f32_e32 v237, v227, v229
	v_mul_f32_e32 v247, v227, v228
	ds_write_b16 v216, v220 offset:512
	ds_write_b16_d16_hi v216, v220 offset:640
	v_fma_f32 v228, v226, v228, -v237
	v_fma_f32 v229, v226, v229, v247
	s_waitcnt lgkmcnt(9)
	v_add_f32_e32 v228, v228, v234
	v_add_f32_e32 v229, v229, v235
	ds_read2st64_b32 v[234:235], v217 offset0:12 offset1:13
	v_cvt_pk_bf16_f32 v220, v228, v229
	v_mul_f32_e32 v237, v227, v229
	v_mul_f32_e32 v247, v227, v228
	ds_write_b16 v216, v220 offset:768
	ds_write_b16_d16_hi v216, v220 offset:896
	v_fma_f32 v228, v226, v228, -v237
	v_fma_f32 v229, v226, v229, v247
	s_waitcnt lgkmcnt(11)
; DEV bf16_t f2bf(float f) { unsigned u = __float_as_uint(f); u += 0x7fffu + ((u >> 16) & 1u); return (bf16_t)(u >> 16); }
; DEV void s5_task(int l, int b, int g, int wave, int lane, LAS unsigned char* sm, unsigned char* ws, float* out, const float* dskip) {
;     ...
;         for (int n = 0; n < 64; ++n) { Hin[n * 128 + lane] = f2bf(hr); Hin[n * 128 + 64 + lane] = f2bf(hi);
;             const float lr = Hloc[n * 128 + lane], li = Hloc[n * 128 + 64 + lane];
;             const float nr = aL.x * hr - aL.y * hi + lr, ni = aL.x * hi + aL.y * hr + li; hr = nr; hi = ni; }
	v_add_f32_e32 v228, v228, v238
	v_add_f32_e32 v229, v229, v239
	ds_read2st64_b32 v[238:239], v217 offset0:14 offset1:15
	v_cvt_pk_bf16_f32 v220, v228, v229
	v_mul_f32_e32 v237, v227, v229
	v_mul_f32_e32 v247, v227, v228
	ds_write_b16 v216, v220 offset:1024
	ds_write_b16_d16_hi v216, v220 offset:1152
	v_fma_f32 v228, v226, v228, -v237
	v_fma_f32 v229, v226, v229, v247
	s_waitcnt lgkmcnt(11)
	v_add_f32_e32 v228, v228, v230
	v_add_f32_e32 v229, v229, v231
	ds_read2st64_b32 v[230:231], v217 offset0:16 offset1:17
	v_cvt_pk_bf16_f32 v220, v228, v229
	v_mul_f32_e32 v237, v227, v229
	v_mul_f32_e32 v247, v227, v228
	ds_write_b16 v216, v220 offset:1280
	ds_write_b16_d16_hi v216, v220 offset:1408
	v_fma_f32 v228, v226, v228, -v237
	v_fma_f32 v229, v226, v229, v247
	s_waitcnt lgkmcnt(11)
	v_add_f32_e32 v228, v228, v232
	v_add_f32_e32 v229, v229, v233
	ds_read2st64_b32 v[232:233], v217 offset0:18 offset1:19
	v_cvt_pk_bf16_f32 v220, v228, v229
	v_mul_f32_e32 v237, v227, v229
	v_mul_f32_e32 v247, v227, v228
	ds_write_b16 v216, v220 offset:1536
	ds_write_b16_d16_hi v216, v220 offset:1664
	v_fma_f32 v228, v226, v228, -v237
	v_fma_f32 v229, v226, v229, v247
	s_waitcnt lgkmcnt(11)
	v_add_f32_e32 v228, v228, v234
	v_add_f32_e32 v229, v229, v235
	ds_read2st64_b32 v[234:235], v217 offset0:20 offset1:21
	v_cvt_pk_bf16_f32 v220, v228, v229
	v_mul_f32_e32 v237, v227, v229
	v_mul_f32_e32 v247, v227, v228
	ds_write_b16 v216, v220 offset:1792
	ds_write_b16_d16_hi v216, v220 offset:1920
	v_fma_f32 v228, v226, v228, -v237
	v_fma_f32 v229, v226, v229, v247
	s_waitcnt lgkmcnt(11)
	v_add_f32_e32 v228, v228, v238
	v_add_f32_e32 v229, v229, v239
	ds_read2st64_b32 v[238:239], v217 offset0:22 offset1:23
	v_cvt_pk_bf16_f32 v220, v228, v229
	v_mul_f32_e32 v237, v227, v229
	v_mul_f32_e32 v247, v227, v228
	ds_write_b16 v216, v220 offset:2048
	ds_write_b16_d16_hi v216, v220 offset:2176
	v_fma_f32 v228, v226, v228, -v237
	v_fma_f32 v229, v226, v229, v247
	s_waitcnt lgkmcnt(11)
	v_add_f32_e32 v228, v228, v230
	v_add_f32_e32 v229, v229, v231
	ds_read2st64_b32 v[230:231], v217 offset0:24 offset1:25
	v_cvt_pk_bf16_f32 v220, v228, v229
	v_mul_f32_e32 v237, v227, v229
	v_mul_f32_e32 v247, v227, v228
	ds_write_b16 v216, v220 offset:2304
	ds_write_b16_d16_hi v216, v220 offset:2432
	v_fma_f32 v228, v226, v228, -v237
	v_fma_f32 v229, v226, v229, v247
	s_waitcnt lgkmcnt(11)
	v_add_f32_e32 v228, v228, v232
	v_add_f32_e32 v229, v229, v233
	ds_read2st64_b32 v[232:233], v217 offset0:26 offset1:27
	v_cvt_pk_bf16_f32 v220, v228, v229
	v_mul_f32_e32 v237, v227, v229
	v_mul_f32_e32 v247, v227, v228
	ds_write_b16 v216, v220 offset:2560
	ds_write_b16_d16_hi v216, v220 offset:2688
	v_fma_f32 v228, v226, v228, -v237
	v_fma_f32 v229, v226, v229, v247
	s_waitcnt lgkmcnt(11)
	v_add_f32_e32 v228, v228, v234
	v_add_f32_e32 v229, v229, v235
	ds_read2st64_b32 v[234:235], v217 offset0:28 offset1:29
	v_cvt_pk_bf16_f32 v220, v228, v229
	v_mul_f32_e32 v237, v227, v229
	v_mul_f32_e32 v247, v227, v228
	ds_write_b16 v216, v220 offset:2816
	ds_write_b16_d16_hi v216, v220 offset:2944
	v_fma_f32 v228, v226, v228, -v237
	v_fma_f32 v229, v226, v229, v247
	s_waitcnt lgkmcnt(11)
	v_add_f32_e32 v228, v228, v238
	v_add_f32_e32 v229, v229, v239
	ds_read2st64_b32 v[238:239], v217 offset0:30 offset1:31
	v_cvt_pk_bf16_f32 v220, v228, v229
	v_mul_f32_e32 v237, v227, v229
	v_mul_f32_e32 v247, v227, v228
	ds_write_b16 v216, v220 offset:3072
	ds_write_b16_d16_hi v216, v220 offset:3200
	v_fma_f32 v228, v226, v228, -v237
	v_fma_f32 v229, v226, v229, v247
	s_waitcnt lgkmcnt(11)
	v_add_f32_e32 v228, v228, v230
	v_add_f32_e32 v229, v229, v231
	ds_read2st64_b32 v[230:231], v217 offset0:32 offset1:33
	v_cvt_pk_bf16_f32 v220, v228, v229
	v_mul_f32_e32 v237, v227, v229
	v_mul_f32_e32 v247, v227, v228
	ds_write_b16 v216, v220 offset:3328
	ds_write_b16_d16_hi v216, v220 offset:3456
	v_fma_f32 v228, v226, v228, -v237
	v_fma_f32 v229, v226, v229, v247
	s_waitcnt lgkmcnt(11)
	v_add_f32_e32 v228, v228, v232
	v_add_f32_e32 v229, v229, v233
	ds_read2st64_b32 v[232:233], v217 offset0:34 offset1:35
	v_cvt_pk_bf16_f32 v220, v228, v229
	v_mul_f32_e32 v237, v227, v229
	v_mul_f32_e32 v247, v227, v228
	ds_write_b16 v216, v220 offset:3584
	ds_write_b16_d16_hi v216, v220 offset:3712
	v_fma_f32 v228, v226, v228, -v237
	v_fma_f32 v229, v226, v229, v247
	s_waitcnt lgkmcnt(11)
	v_add_f32_e32 v228, v228, v234
	v_add_f32_e32 v229, v229, v235
	ds_read2st64_b32 v[234:235], v217 offset0:36 offset1:37
	v_cvt_pk_bf16_f32 v220, v228, v229
	v_mul_f32_e32 v237, v227, v229
	v_mul_f32_e32 v247, v227, v228
	ds_write_b16 v216, v220 offset:3840
	ds_write_b16_d16_hi v216, v220 offset:3968
	v_fma_f32 v228, v226, v228, -v237
	v_fma_f32 v229, v226, v229, v247
	s_waitcnt lgkmcnt(11)
	v_add_f32_e32 v228, v228, v238
	v_add_f32_e32 v229, v229, v239
	ds_read2st64_b32 v[238:239], v217 offset0:38 offset1:39
	v_cvt_pk_bf16_f32 v220, v228, v229
	v_mul_f32_e32 v237, v227, v229
	v_mul_f32_e32 v247, v227, v228
	ds_write_b16 v216, v220 offset:4096
	ds_write_b16_d16_hi v216, v220 offset:4224
	v_fma_f32 v228, v226, v228, -v237
	v_fma_f32 v229, v226, v229, v247
	s_waitcnt lgkmcnt(11)
	v_add_f32_e32 v228, v228, v230
	v_add_f32_e32 v229, v229, v231
	ds_read2st64_b32 v[230:231], v217 offset0:40 offset1:41
	v_cvt_pk_bf16_f32 v220, v228, v229
	v_mul_f32_e32 v237, v227, v229
	v_mul_f32_e32 v247, v227, v228
	ds_write_b16 v216, v220 offset:4352
	ds_write_b16_d16_hi v216, v220 offset:4480
	v_fma_f32 v228, v226, v228, -v237
	v_fma_f32 v229, v226, v229, v247
	s_waitcnt lgkmcnt(11)
; DEV bf16_t f2bf(float f) { unsigned u = __float_as_uint(f); u += 0x7fffu + ((u >> 16) & 1u); return (bf16_t)(u >> 16); }
; DEV void s5_task(int l, int b, int g, int wave, int lane, LAS unsigned char* sm, unsigned char* ws, float* out, const float* dskip) {
;     ...
;         for (int n = 0; n < 64; ++n) { Hin[n * 128 + lane] = f2bf(hr); Hin[n * 128 + 64 + lane] = f2bf(hi);
;             const float lr = Hloc[n * 128 + lane], li = Hloc[n * 128 + 64 + lane];
;             const float nr = aL.x * hr - aL.y * hi + lr, ni = aL.x * hi + aL.y * hr + li; hr = nr; hi = ni; }
	v_add_f32_e32 v228, v228, v232
	v_add_f32_e32 v229, v229, v233
	ds_read2st64_b32 v[232:233], v217 offset0:42 offset1:43
	v_cvt_pk_bf16_f32 v220, v228, v229
	v_mul_f32_e32 v237, v227, v229
	v_mul_f32_e32 v247, v227, v228
	ds_write_b16 v216, v220 offset:4608
	ds_write_b16_d16_hi v216, v220 offset:4736
	v_fma_f32 v228, v226, v228, -v237
	v_fma_f32 v229, v226, v229, v247
	s_waitcnt lgkmcnt(11)
	v_add_f32_e32 v228, v228, v234
	v_add_f32_e32 v229, v229, v235
	ds_read2st64_b32 v[234:235], v217 offset0:44 offset1:45
	v_cvt_pk_bf16_f32 v220, v228, v229
	v_mul_f32_e32 v237, v227, v229
	v_mul_f32_e32 v247, v227, v228
	ds_write_b16 v216, v220 offset:4864
	ds_write_b16_d16_hi v216, v220 offset:4992
	v_fma_f32 v228, v226, v228, -v237
	v_fma_f32 v229, v226, v229, v247
	s_waitcnt lgkmcnt(11)
	v_add_f32_e32 v228, v228, v238
	v_add_f32_e32 v229, v229, v239
	ds_read2st64_b32 v[238:239], v217 offset0:46 offset1:47
	v_cvt_pk_bf16_f32 v220, v228, v229
	v_mul_f32_e32 v237, v227, v229
	v_mul_f32_e32 v247, v227, v228
	ds_write_b16 v216, v220 offset:5120
	ds_write_b16_d16_hi v216, v220 offset:5248
	v_fma_f32 v228, v226, v228, -v237
	v_fma_f32 v229, v226, v229, v247
	s_waitcnt lgkmcnt(11)
	v_add_f32_e32 v228, v228, v230
	v_add_f32_e32 v229, v229, v231
	ds_read2st64_b32 v[230:231], v217 offset0:48 offset1:49
	v_cvt_pk_bf16_f32 v220, v228, v229
	v_mul_f32_e32 v237, v227, v229
	v_mul_f32_e32 v247, v227, v228
	ds_write_b16 v216, v220 offset:5376
	ds_write_b16_d16_hi v216, v220 offset:5504
	v_fma_f32 v228, v226, v228, -v237
	v_fma_f32 v229, v226, v229, v247
	s_waitcnt lgkmcnt(11)
	v_add_f32_e32 v228, v228, v232
	v_add_f32_e32 v229, v229, v233
	ds_read2st64_b32 v[232:233], v217 offset0:50 offset1:51
	v_cvt_pk_bf16_f32 v220, v228, v229
	v_mul_f32_e32 v237, v227, v229
	v_mul_f32_e32 v247, v227, v228
	ds_write_b16 v216, v220 offset:5632
	ds_write_b16_d16_hi v216, v220 offset:5760
	v_fma_f32 v228, v226, v228, -v237
	v_fma_f32 v229, v226, v229, v247
	s_waitcnt lgkmcnt(11)
	v_add_f32_e32 v228, v228, v234
	v_add_f32_e32 v229, v229, v235
	ds_read2st64_b32 v[234:235], v217 offset0:52 offset1:53
	v_cvt_pk_bf16_f32 v220, v228, v229
	v_mul_f32_e32 v237, v227, v229
	v_mul_f32_e32 v247, v227, v228
	ds_write_b16 v216, v220 offset:5888
	ds_write_b16_d16_hi v216, v220 offset:6016
	v_fma_f32 v228, v226, v228, -v237
	v_fma_f32 v229, v226, v229, v247
	s_waitcnt lgkmcnt(11)
	v_add_f32_e32 v228, v228, v238
	v_add_f32_e32 v229, v229, v239
	ds_read2st64_b32 v[238:239], v217 offset0:54 offset1:55
	v_cvt_pk_bf16_f32 v220, v228, v229
	v_mul_f32_e32 v237, v227, v229
	v_mul_f32_e32 v247, v227, v228
	ds_write_b16 v216, v220 offset:6144
	ds_write_b16_d16_hi v216, v220 offset:6272
	v_fma_f32 v228, v226, v228, -v237
	v_fma_f32 v229, v226, v229, v247
	s_waitcnt lgkmcnt(11)
	v_add_f32_e32 v228, v228, v230
	v_add_f32_e32 v229, v229, v231
	ds_read2st64_b32 v[230:231], v217 offset0:56 offset1:57
	v_cvt_pk_bf16_f32 v220, v228, v229
	v_mul_f32_e32 v237, v227, v229
	v_mul_f32_e32 v247, v227, v228
	ds_write_b16 v216, v220 offset:6400
	ds_write_b16_d16_hi v216, v220 offset:6528
	v_fma_f32 v228, v226, v228, -v237
	v_fma_f32 v229, v226, v229, v247
	s_waitcnt lgkmcnt(11)
	v_add_f32_e32 v228, v228, v232
	v_add_f32_e32 v229, v229, v233
	ds_read2st64_b32 v[232:233], v217 offset0:58 offset1:59
	v_cvt_pk_bf16_f32 v220, v228, v229
	v_mul_f32_e32 v237, v227, v229
	v_mul_f32_e32 v247, v227, v228
	ds_write_b16 v216, v220 offset:6656
	ds_write_b16_d16_hi v216, v220 offset:6784
	v_fma_f32 v228, v226, v228, -v237
	v_fma_f32 v229, v226, v229, v247
	s_waitcnt lgkmcnt(11)
	v_add_f32_e32 v228, v228, v234
	v_add_f32_e32 v229, v229, v235
	ds_read2st64_b32 v[234:235], v217 offset0:60 offset1:61
	v_cvt_pk_bf16_f32 v220, v228, v229
	v_mul_f32_e32 v237, v227, v229
	v_mul_f32_e32 v247, v227, v228
	ds_write_b16 v216, v220 offset:6912
	ds_write_b16_d16_hi v216, v220 offset:7040
	v_fma_f32 v228, v226, v228, -v237
	v_fma_f32 v229, v226, v229, v247
	s_waitcnt lgkmcnt(11)
	v_add_f32_e32 v228, v228, v238
	v_add_f32_e32 v229, v229, v239
	ds_read2st64_b32 v[238:239], v217 offset0:62 offset1:63
	v_cvt_pk_bf16_f32 v220, v228, v229
	v_mul_f32_e32 v237, v227, v229
	v_mul_f32_e32 v247, v227, v228
	ds_write_b16 v216, v220 offset:7168
	ds_write_b16_d16_hi v216, v220 offset:7296
	v_fma_f32 v228, v226, v228, -v237
	v_fma_f32 v229, v226, v229, v247
	s_waitcnt lgkmcnt(11)
	v_add_f32_e32 v228, v228, v230
	v_add_f32_e32 v229, v229, v231
	ds_read2st64_b32 v[230:231], v217 offset0:64 offset1:65
	v_cvt_pk_bf16_f32 v220, v228, v229
	v_mul_f32_e32 v237, v227, v229
	v_mul_f32_e32 v247, v227, v228
	ds_write_b16 v216, v220 offset:7424
	ds_write_b16_d16_hi v216, v220 offset:7552
	v_fma_f32 v228, v226, v228, -v237
	v_fma_f32 v229, v226, v229, v247
	s_waitcnt lgkmcnt(11)
	v_add_f32_e32 v228, v228, v232
	v_add_f32_e32 v229, v229, v233
	ds_read2st64_b32 v[232:233], v217 offset0:66 offset1:67
	v_cvt_pk_bf16_f32 v220, v228, v229
	v_mul_f32_e32 v237, v227, v229
	v_mul_f32_e32 v247, v227, v228
	ds_write_b16 v216, v220 offset:7680
	ds_write_b16_d16_hi v216, v220 offset:7808
	v_fma_f32 v228, v226, v228, -v237
	v_fma_f32 v229, v226, v229, v247
	s_waitcnt lgkmcnt(11)
	v_add_f32_e32 v228, v228, v234
	v_add_f32_e32 v229, v229, v235
	ds_read2st64_b32 v[234:235], v217 offset0:68 offset1:69
	v_cvt_pk_bf16_f32 v220, v228, v229
	v_mul_f32_e32 v237, v227, v229
	v_mul_f32_e32 v247, v227, v228
	ds_write_b16 v216, v220 offset:7936
	ds_write_b16_d16_hi v216, v220 offset:8064
	v_fma_f32 v228, v226, v228, -v237
	v_fma_f32 v229, v226, v229, v247
	s_waitcnt lgkmcnt(11)
; DEV bf16_t f2bf(float f) { unsigned u = __float_as_uint(f); u += 0x7fffu + ((u >> 16) & 1u); return (bf16_t)(u >> 16); }
; DEV void s5_task(int l, int b, int g, int wave, int lane, LAS unsigned char* sm, unsigned char* ws, float* out, const float* dskip) {
;     ...
;         for (int n = 0; n < 64; ++n) { Hin[n * 128 + lane] = f2bf(hr); Hin[n * 128 + 64 + lane] = f2bf(hi);
;             const float lr = Hloc[n * 128 + lane], li = Hloc[n * 128 + 64 + lane];
;             const float nr = aL.x * hr - aL.y * hi + lr, ni = aL.x * hi + aL.y * hr + li; hr = nr; hi = ni; }
	v_add_f32_e32 v228, v228, v238
	v_add_f32_e32 v229, v229, v239
	ds_read2st64_b32 v[238:239], v217 offset0:70 offset1:71
	v_cvt_pk_bf16_f32 v220, v228, v229
	v_mul_f32_e32 v237, v227, v229
	v_mul_f32_e32 v247, v227, v228
	ds_write_b16 v216, v220 offset:8192
	ds_write_b16_d16_hi v216, v220 offset:8320
	v_fma_f32 v228, v226, v228, -v237
	v_fma_f32 v229, v226, v229, v247
	s_waitcnt lgkmcnt(11)
	v_add_f32_e32 v228, v228, v230
	v_add_f32_e32 v229, v229, v231
	ds_read2st64_b32 v[230:231], v217 offset0:72 offset1:73
	v_cvt_pk_bf16_f32 v220, v228, v229
	v_mul_f32_e32 v237, v227, v229
	v_mul_f32_e32 v247, v227, v228
	ds_write_b16 v216, v220 offset:8448
	ds_write_b16_d16_hi v216, v220 offset:8576
	v_fma_f32 v228, v226, v228, -v237
	v_fma_f32 v229, v226, v229, v247
	s_waitcnt lgkmcnt(11)
	v_add_f32_e32 v228, v228, v232
	v_add_f32_e32 v229, v229, v233
	ds_read2st64_b32 v[232:233], v217 offset0:74 offset1:75
	v_cvt_pk_bf16_f32 v220, v228, v229
	v_mul_f32_e32 v237, v227, v229
	v_mul_f32_e32 v247, v227, v228
	ds_write_b16 v216, v220 offset:8704
	ds_write_b16_d16_hi v216, v220 offset:8832
	v_fma_f32 v228, v226, v228, -v237
	v_fma_f32 v229, v226, v229, v247
	s_waitcnt lgkmcnt(11)
	v_add_f32_e32 v228, v228, v234
	v_add_f32_e32 v229, v229, v235
	ds_read2st64_b32 v[234:235], v217 offset0:76 offset1:77
	v_cvt_pk_bf16_f32 v220, v228, v229
	v_mul_f32_e32 v237, v227, v229
	v_mul_f32_e32 v247, v227, v228
	ds_write_b16 v216, v220 offset:8960
	ds_write_b16_d16_hi v216, v220 offset:9088
	v_fma_f32 v228, v226, v228, -v237
	v_fma_f32 v229, v226, v229, v247
	s_waitcnt lgkmcnt(11)
	v_add_f32_e32 v228, v228, v238
	v_add_f32_e32 v229, v229, v239
	ds_read2st64_b32 v[238:239], v217 offset0:78 offset1:79
	v_cvt_pk_bf16_f32 v220, v228, v229
	v_mul_f32_e32 v237, v227, v229
	v_mul_f32_e32 v247, v227, v228
	ds_write_b16 v216, v220 offset:9216
	ds_write_b16_d16_hi v216, v220 offset:9344
	v_fma_f32 v228, v226, v228, -v237
	v_fma_f32 v229, v226, v229, v247
	s_waitcnt lgkmcnt(11)
	v_add_f32_e32 v228, v228, v230
	v_add_f32_e32 v229, v229, v231
	ds_read2st64_b32 v[230:231], v217 offset0:80 offset1:81
	v_cvt_pk_bf16_f32 v220, v228, v229
	v_mul_f32_e32 v237, v227, v229
	v_mul_f32_e32 v247, v227, v228
	ds_write_b16 v216, v220 offset:9472
	ds_write_b16_d16_hi v216, v220 offset:9600
	v_fma_f32 v228, v226, v228, -v237
	v_fma_f32 v229, v226, v229, v247
	s_waitcnt lgkmcnt(11)
	v_add_f32_e32 v228, v228, v232
	v_add_f32_e32 v229, v229, v233
	ds_read2st64_b32 v[232:233], v217 offset0:82 offset1:83
	v_cvt_pk_bf16_f32 v220, v228, v229
	v_mul_f32_e32 v237, v227, v229
	v_mul_f32_e32 v247, v227, v228
	ds_write_b16 v216, v220 offset:9728
	ds_write_b16_d16_hi v216, v220 offset:9856
	v_fma_f32 v228, v226, v228, -v237
	v_fma_f32 v229, v226, v229, v247
	s_waitcnt lgkmcnt(11)
	v_add_f32_e32 v228, v228, v234
	v_add_f32_e32 v229, v229, v235
	ds_read2st64_b32 v[234:235], v217 offset0:84 offset1:85
	v_cvt_pk_bf16_f32 v220, v228, v229
	v_mul_f32_e32 v237, v227, v229
	v_mul_f32_e32 v247, v227, v228
	ds_write_b16 v216, v220 offset:9984
	ds_write_b16_d16_hi v216, v220 offset:10112
	v_fma_f32 v228, v226, v228, -v237
	v_fma_f32 v229, v226, v229, v247
	s_waitcnt lgkmcnt(11)
	v_add_f32_e32 v228, v228, v238
	v_add_f32_e32 v229, v229, v239
	ds_read2st64_b32 v[238:239], v217 offset0:86 offset1:87
	v_cvt_pk_bf16_f32 v220, v228, v229
	v_mul_f32_e32 v237, v227, v229
	v_mul_f32_e32 v247, v227, v228
	ds_write_b16 v216, v220 offset:10240
	ds_write_b16_d16_hi v216, v220 offset:10368
	v_fma_f32 v228, v226, v228, -v237
	v_fma_f32 v229, v226, v229, v247
	s_waitcnt lgkmcnt(11)
	v_add_f32_e32 v228, v228, v230
	v_add_f32_e32 v229, v229, v231
	ds_read2st64_b32 v[230:231], v217 offset0:88 offset1:89
	v_cvt_pk_bf16_f32 v220, v228, v229
	v_mul_f32_e32 v237, v227, v229
	v_mul_f32_e32 v247, v227, v228
	ds_write_b16 v216, v220 offset:10496
	ds_write_b16_d16_hi v216, v220 offset:10624
	v_fma_f32 v228, v226, v228, -v237
	v_fma_f32 v229, v226, v229, v247
	s_waitcnt lgkmcnt(11)
	v_add_f32_e32 v228, v228, v232
	v_add_f32_e32 v229, v229, v233
	ds_read2st64_b32 v[232:233], v217 offset0:90 offset1:91
	v_cvt_pk_bf16_f32 v220, v228, v229
	v_mul_f32_e32 v237, v227, v229
	v_mul_f32_e32 v247, v227, v228
	ds_write_b16 v216, v220 offset:10752
	ds_write_b16_d16_hi v216, v220 offset:10880
	v_fma_f32 v228, v226, v228, -v237
	v_fma_f32 v229, v226, v229, v247
	s_waitcnt lgkmcnt(11)
	v_add_f32_e32 v228, v228, v234
	v_add_f32_e32 v229, v229, v235
	ds_read2st64_b32 v[234:235], v217 offset0:92 offset1:93
	v_cvt_pk_bf16_f32 v220, v228, v229
	v_mul_f32_e32 v237, v227, v229
	v_mul_f32_e32 v247, v227, v228
	ds_write_b16 v216, v220 offset:11008
	ds_write_b16_d16_hi v216, v220 offset:11136
	v_fma_f32 v228, v226, v228, -v237
	v_fma_f32 v229, v226, v229, v247
	s_waitcnt lgkmcnt(11)
	v_add_f32_e32 v228, v228, v238
	v_add_f32_e32 v229, v229, v239
	ds_read2st64_b32 v[238:239], v217 offset0:94 offset1:95
	v_cvt_pk_bf16_f32 v220, v228, v229
	v_mul_f32_e32 v237, v227, v229
	v_mul_f32_e32 v247, v227, v228
	ds_write_b16 v216, v220 offset:11264
	ds_write_b16_d16_hi v216, v220 offset:11392
	v_fma_f32 v228, v226, v228, -v237
	v_fma_f32 v229, v226, v229, v247
	s_waitcnt lgkmcnt(11)
	v_add_f32_e32 v228, v228, v230
	v_add_f32_e32 v229, v229, v231
	ds_read2st64_b32 v[230:231], v217 offset0:96 offset1:97
	v_cvt_pk_bf16_f32 v220, v228, v229
	v_mul_f32_e32 v237, v227, v229
	v_mul_f32_e32 v247, v227, v228
	ds_write_b16 v216, v220 offset:11520
	ds_write_b16_d16_hi v216, v220 offset:11648
	v_fma_f32 v228, v226, v228, -v237
	v_fma_f32 v229, v226, v229, v247
	s_waitcnt lgkmcnt(11)
; DEV bf16_t f2bf(float f) { unsigned u = __float_as_uint(f); u += 0x7fffu + ((u >> 16) & 1u); return (bf16_t)(u >> 16); }
; DEV void s5_task(int l, int b, int g, int wave, int lane, LAS unsigned char* sm, unsigned char* ws, float* out, const float* dskip) {
;     ...
;         for (int n = 0; n < 64; ++n) { Hin[n * 128 + lane] = f2bf(hr); Hin[n * 128 + 64 + lane] = f2bf(hi);
;             const float lr = Hloc[n * 128 + lane], li = Hloc[n * 128 + 64 + lane];
;             const float nr = aL.x * hr - aL.y * hi + lr, ni = aL.x * hi + aL.y * hr + li; hr = nr; hi = ni; }
	v_add_f32_e32 v228, v228, v232
	v_add_f32_e32 v229, v229, v233
	ds_read2st64_b32 v[232:233], v217 offset0:98 offset1:99
	v_cvt_pk_bf16_f32 v220, v228, v229
	v_mul_f32_e32 v237, v227, v229
	v_mul_f32_e32 v247, v227, v228
	ds_write_b16 v216, v220 offset:11776
	ds_write_b16_d16_hi v216, v220 offset:11904
	v_fma_f32 v228, v226, v228, -v237
	v_fma_f32 v229, v226, v229, v247
	s_waitcnt lgkmcnt(11)
	v_add_f32_e32 v228, v228, v234
	v_add_f32_e32 v229, v229, v235
	ds_read2st64_b32 v[234:235], v217 offset0:100 offset1:101
	v_cvt_pk_bf16_f32 v220, v228, v229
	v_mul_f32_e32 v237, v227, v229
	v_mul_f32_e32 v247, v227, v228
	ds_write_b16 v216, v220 offset:12032
	ds_write_b16_d16_hi v216, v220 offset:12160
	v_fma_f32 v228, v226, v228, -v237
	v_fma_f32 v229, v226, v229, v247
	s_waitcnt lgkmcnt(11)
	v_add_f32_e32 v228, v228, v238
	v_add_f32_e32 v229, v229, v239
	ds_read2st64_b32 v[238:239], v217 offset0:102 offset1:103
	v_cvt_pk_bf16_f32 v220, v228, v229
	v_mul_f32_e32 v237, v227, v229
	v_mul_f32_e32 v247, v227, v228
	ds_write_b16 v216, v220 offset:12288
	ds_write_b16_d16_hi v216, v220 offset:12416
	v_fma_f32 v228, v226, v228, -v237
	v_fma_f32 v229, v226, v229, v247
	s_waitcnt lgkmcnt(11)
	v_add_f32_e32 v228, v228, v230
	v_add_f32_e32 v229, v229, v231
	ds_read2st64_b32 v[230:231], v217 offset0:104 offset1:105
	v_cvt_pk_bf16_f32 v220, v228, v229
	v_mul_f32_e32 v237, v227, v229
	v_mul_f32_e32 v247, v227, v228
	ds_write_b16 v216, v220 offset:12544
	ds_write_b16_d16_hi v216, v220 offset:12672
	v_fma_f32 v228, v226, v228, -v237
	v_fma_f32 v229, v226, v229, v247
	s_waitcnt lgkmcnt(11)
	v_add_f32_e32 v228, v228, v232
	v_add_f32_e32 v229, v229, v233
	ds_read2st64_b32 v[232:233], v217 offset0:106 offset1:107
	v_cvt_pk_bf16_f32 v220, v228, v229
	v_mul_f32_e32 v237, v227, v229
	v_mul_f32_e32 v247, v227, v228
	ds_write_b16 v216, v220 offset:12800
	ds_write_b16_d16_hi v216, v220 offset:12928
	v_fma_f32 v228, v226, v228, -v237
	v_fma_f32 v229, v226, v229, v247
	s_waitcnt lgkmcnt(11)
	v_add_f32_e32 v228, v228, v234
	v_add_f32_e32 v229, v229, v235
	ds_read2st64_b32 v[234:235], v217 offset0:108 offset1:109
	v_cvt_pk_bf16_f32 v220, v228, v229
	v_mul_f32_e32 v237, v227, v229
	v_mul_f32_e32 v247, v227, v228
	ds_write_b16 v216, v220 offset:13056
	ds_write_b16_d16_hi v216, v220 offset:13184
	v_fma_f32 v228, v226, v228, -v237
	v_fma_f32 v229, v226, v229, v247
	s_waitcnt lgkmcnt(11)
	v_add_f32_e32 v228, v228, v238
	v_add_f32_e32 v229, v229, v239
	ds_read2st64_b32 v[238:239], v217 offset0:110 offset1:111
	v_cvt_pk_bf16_f32 v220, v228, v229
	v_mul_f32_e32 v237, v227, v229
	v_mul_f32_e32 v247, v227, v228
	ds_write_b16 v216, v220 offset:13312
	ds_write_b16_d16_hi v216, v220 offset:13440
	v_fma_f32 v228, v226, v228, -v237
	v_fma_f32 v229, v226, v229, v247
	s_waitcnt lgkmcnt(11)
	v_add_f32_e32 v228, v228, v230
	v_add_f32_e32 v229, v229, v231
	ds_read2st64_b32 v[230:231], v217 offset0:112 offset1:113
	v_cvt_pk_bf16_f32 v220, v228, v229
	v_mul_f32_e32 v237, v227, v229
	v_mul_f32_e32 v247, v227, v228
	ds_write_b16 v216, v220 offset:13568
	ds_write_b16_d16_hi v216, v220 offset:13696
	v_fma_f32 v228, v226, v228, -v237
	v_fma_f32 v229, v226, v229, v247
	s_waitcnt lgkmcnt(11)
	v_add_f32_e32 v228, v228, v232
	v_add_f32_e32 v229, v229, v233
	ds_read2st64_b32 v[232:233], v217 offset0:114 offset1:115
	v_cvt_pk_bf16_f32 v220, v228, v229
	v_mul_f32_e32 v237, v227, v229
	v_mul_f32_e32 v247, v227, v228
	ds_write_b16 v216, v220 offset:13824
	ds_write_b16_d16_hi v216, v220 offset:13952
	v_fma_f32 v228, v226, v228, -v237
	v_fma_f32 v229, v226, v229, v247
	s_waitcnt lgkmcnt(11)
	v_add_f32_e32 v228, v228, v234
	v_add_f32_e32 v229, v229, v235
	ds_read2st64_b32 v[234:235], v217 offset0:116 offset1:117
	v_cvt_pk_bf16_f32 v220, v228, v229
	v_mul_f32_e32 v237, v227, v229
	v_mul_f32_e32 v247, v227, v228
	ds_write_b16 v216, v220 offset:14080
	ds_write_b16_d16_hi v216, v220 offset:14208
	v_fma_f32 v228, v226, v228, -v237
	v_fma_f32 v229, v226, v229, v247
	s_waitcnt lgkmcnt(11)
	v_add_f32_e32 v228, v228, v238
	v_add_f32_e32 v229, v229, v239
	ds_read2st64_b32 v[238:239], v217 offset0:118 offset1:119
	v_cvt_pk_bf16_f32 v220, v228, v229
	v_mul_f32_e32 v237, v227, v229
	v_mul_f32_e32 v247, v227, v228
	ds_write_b16 v216, v220 offset:14336
	ds_write_b16_d16_hi v216, v220 offset:14464
	v_fma_f32 v228, v226, v228, -v237
	v_fma_f32 v229, v226, v229, v247
	s_waitcnt lgkmcnt(11)
	v_add_f32_e32 v228, v228, v230
	v_add_f32_e32 v229, v229, v231
	ds_read2st64_b32 v[230:231], v217 offset0:120 offset1:121
	v_cvt_pk_bf16_f32 v220, v228, v229
	v_mul_f32_e32 v237, v227, v229
	v_mul_f32_e32 v247, v227, v228
	ds_write_b16 v216, v220 offset:14592
	ds_write_b16_d16_hi v216, v220 offset:14720
	v_fma_f32 v228, v226, v228, -v237
	v_fma_f32 v229, v226, v229, v247
	s_waitcnt lgkmcnt(11)
	v_add_f32_e32 v228, v228, v232
	v_add_f32_e32 v229, v229, v233
	ds_read2st64_b32 v[232:233], v217 offset0:122 offset1:123
	v_cvt_pk_bf16_f32 v220, v228, v229
	v_mul_f32_e32 v237, v227, v229
	v_mul_f32_e32 v247, v227, v228
	ds_write_b16 v216, v220 offset:14848
	ds_write_b16_d16_hi v216, v220 offset:14976
	v_fma_f32 v228, v226, v228, -v237
	v_fma_f32 v229, v226, v229, v247
	s_waitcnt lgkmcnt(11)
	v_add_f32_e32 v228, v228, v234
	v_add_f32_e32 v229, v229, v235
	ds_read2st64_b32 v[234:235], v217 offset0:124 offset1:125
	v_cvt_pk_bf16_f32 v220, v228, v229
	v_mul_f32_e32 v237, v227, v229
	v_mul_f32_e32 v247, v227, v228
	ds_write_b16 v216, v220 offset:15104
	ds_write_b16_d16_hi v216, v220 offset:15232
	v_fma_f32 v228, v226, v228, -v237
	v_fma_f32 v229, v226, v229, v247
	s_waitcnt lgkmcnt(11)
; DEV bf16_t f2bf(float f) { unsigned u = __float_as_uint(f); u += 0x7fffu + ((u >> 16) & 1u); return (bf16_t)(u >> 16); }
; #define LAS __attribute__((address_space(3)))
; DEV void s5_task(int l, int b, int g, int wave, int lane, LAS unsigned char* sm, unsigned char* ws, float* out, const float* dskip) {
;     ...
;         for (int n = 0; n < 64; ++n) { Hin[n * 128 + lane] = f2bf(hr); Hin[n * 128 + 64 + lane] = f2bf(hi);
;             const float lr = Hloc[n * 128 + lane], li = Hloc[n * 128 + 64 + lane];
;             const float nr = aL.x * hr - aL.y * hi + lr, ni = aL.x * hi + aL.y * hr + li; hr = nr; hi = ni; }
;         float* o = out + O_S5P + ((((size_t)l * NB + b) * S5G + g) * S5P + lane) * 2; o[0] = hr; o[1] = hi; }
;     __syncthreads();
; #pragma unroll
;     for (int s = 0; s < 4; ++s) { const int k0 = 32 * s + 8 * fq;
;         bf16x8 bfr[4];
; #pragma unroll
;         for (int nt = 0; nt < 4; ++nt) bfr[nt] = *(const LAS bf16x8*)(Hin + (nt * 16 + fr) * 128 + k0);
; #pragma unroll
;         for (int i = 0; i < 4; ++i) { const int rt = wave + 8 * i; const bf16x8 a = *(const bf16x8*)(PM + (size_t)(rt * 16 + fr) * 128 + k0);
; #pragma unroll
;             for (int nt = 0; nt < 4; ++nt) acc[i][nt] = __builtin_amdgcn_mfma_f32_16x16x32_bf16(a, bfr[nt], acc[i][nt], 0, 0, 0); } }
	v_add_f32_e32 v228, v228, v238
	v_add_f32_e32 v229, v229, v239
	ds_read2st64_b32 v[238:239], v217 offset0:126 offset1:127
	v_cvt_pk_bf16_f32 v220, v228, v229
	v_mul_f32_e32 v237, v227, v229
	v_mul_f32_e32 v247, v227, v228
	ds_write_b16 v216, v220 offset:15360
	ds_write_b16_d16_hi v216, v220 offset:15488
	v_fma_f32 v228, v226, v228, -v237
	v_fma_f32 v229, v226, v229, v247
	s_waitcnt lgkmcnt(11)
	v_add_f32_e32 v228, v228, v230
	v_add_f32_e32 v229, v229, v231
	v_cvt_pk_bf16_f32 v220, v228, v229
	v_mul_f32_e32 v237, v227, v229
	v_mul_f32_e32 v247, v227, v228
	ds_write_b16 v216, v220 offset:15616
	ds_write_b16_d16_hi v216, v220 offset:15744
	v_fma_f32 v228, v226, v228, -v237
	v_fma_f32 v229, v226, v229, v247
	s_waitcnt lgkmcnt(10)
	v_add_f32_e32 v228, v228, v232
	v_add_f32_e32 v229, v229, v233
	v_cvt_pk_bf16_f32 v220, v228, v229
	v_mul_f32_e32 v237, v227, v229
	v_mul_f32_e32 v247, v227, v228
	ds_write_b16 v216, v220 offset:15872
	ds_write_b16_d16_hi v216, v220 offset:16000
	v_fma_f32 v228, v226, v228, -v237
	v_fma_f32 v229, v226, v229, v247
	s_waitcnt lgkmcnt(9)
	v_add_f32_e32 v228, v228, v234
	v_add_f32_e32 v229, v229, v235
	v_cvt_pk_bf16_f32 v220, v228, v229
	v_mul_f32_e32 v237, v227, v229
	v_mul_f32_e32 v247, v227, v228
	ds_write_b16 v216, v220 offset:16128
	ds_write_b16_d16_hi v216, v220 offset:16256
	v_fma_f32 v228, v226, v228, -v237
	v_fma_f32 v229, v226, v229, v247
	s_waitcnt lgkmcnt(8)
	v_add_f32_e32 v228, v228, v238
	v_add_f32_e32 v229, v229, v239
	s_lshl_b32 s3, s22, 3
	s_add_i32 s3, s3, s20
	s_lshl_b32 s3, s3, 9
	s_add_u32 s6, s24, s3
	s_addc_u32 s7, s25, 0
	s_add_u32 s6, s6, 0x6820000
	s_addc_u32 s7, s7, 0
	v_lshlrev_b32_e32 v220, 3, v116
	global_store_dwordx2 v220, v[228:229], s[6:7]
.Ls5s_noscan:
	s_waitcnt lgkmcnt(0)
	s_barrier
	s_waitcnt vmcnt(17)
	ds_read_b128 v[198:201], v218 offset:0
	ds_read_b128 v[202:205], v218 offset:4096
	ds_read_b128 v[206:209], v218 offset:8192
	ds_read_b128 v[210:213], v218 offset:12288
	s_waitcnt lgkmcnt(3)
	v_mfma_f32_16x16x32_bf16 v[2:5], v[122:125], v[198:201], v[2:5]
	s_waitcnt lgkmcnt(2)
	v_mfma_f32_16x16x32_bf16 v[6:9], v[122:125], v[202:205], v[6:9]
	s_waitcnt lgkmcnt(1)
	v_mfma_f32_16x16x32_bf16 v[10:13], v[122:125], v[206:209], v[10:13]
	s_waitcnt lgkmcnt(0)
	v_mfma_f32_16x16x32_bf16 v[14:17], v[122:125], v[210:213], v[14:17]
	v_mfma_f32_16x16x32_bf16 v[18:21], v[126:129], v[198:201], v[18:21]
	v_mfma_f32_16x16x32_bf16 v[22:25], v[126:129], v[202:205], v[22:25]
	v_mfma_f32_16x16x32_bf16 v[26:29], v[126:129], v[206:209], v[26:29]
	v_mfma_f32_16x16x32_bf16 v[30:33], v[126:129], v[210:213], v[30:33]
	v_mfma_f32_16x16x32_bf16 v[34:37], v[130:133], v[198:201], v[34:37]
	v_mfma_f32_16x16x32_bf16 v[38:41], v[130:133], v[202:205], v[38:41]
	v_mfma_f32_16x16x32_bf16 v[42:45], v[130:133], v[206:209], v[42:45]
	v_mfma_f32_16x16x32_bf16 v[46:49], v[130:133], v[210:213], v[46:49]
	v_mfma_f32_16x16x32_bf16 v[50:53], v[134:137], v[198:201], v[50:53]
	v_mfma_f32_16x16x32_bf16 v[54:57], v[134:137], v[202:205], v[54:57]
	v_mfma_f32_16x16x32_bf16 v[58:61], v[134:137], v[206:209], v[58:61]
	v_mfma_f32_16x16x32_bf16 v[62:65], v[134:137], v[210:213], v[62:65]
	ds_read_b128 v[198:201], v218 offset:64
	ds_read_b128 v[202:205], v218 offset:4160
	ds_read_b128 v[206:209], v218 offset:8256
	ds_read_b128 v[210:213], v218 offset:12352
	s_waitcnt lgkmcnt(3)
	v_mfma_f32_16x16x32_bf16 v[2:5], v[138:141], v[198:201], v[2:5]
	s_waitcnt lgkmcnt(2)
	v_mfma_f32_16x16x32_bf16 v[6:9], v[138:141], v[202:205], v[6:9]
	s_waitcnt lgkmcnt(1)
	v_mfma_f32_16x16x32_bf16 v[10:13], v[138:141], v[206:209], v[10:13]
	s_waitcnt lgkmcnt(0)
	v_mfma_f32_16x16x32_bf16 v[14:17], v[138:141], v[210:213], v[14:17]
	v_mfma_f32_16x16x32_bf16 v[18:21], v[142:145], v[198:201], v[18:21]
	v_mfma_f32_16x16x32_bf16 v[22:25], v[142:145], v[202:205], v[22:25]
	v_mfma_f32_16x16x32_bf16 v[26:29], v[142:145], v[206:209], v[26:29]
	v_mfma_f32_16x16x32_bf16 v[30:33], v[142:145], v[210:213], v[30:33]
	v_mfma_f32_16x16x32_bf16 v[34:37], v[146:149], v[198:201], v[34:37]
	v_mfma_f32_16x16x32_bf16 v[38:41], v[146:149], v[202:205], v[38:41]
	v_mfma_f32_16x16x32_bf16 v[42:45], v[146:149], v[206:209], v[42:45]
	v_mfma_f32_16x16x32_bf16 v[46:49], v[146:149], v[210:213], v[46:49]
	v_mfma_f32_16x16x32_bf16 v[50:53], v[150:153], v[198:201], v[50:53]
	v_mfma_f32_16x16x32_bf16 v[54:57], v[150:153], v[202:205], v[54:57]
	v_mfma_f32_16x16x32_bf16 v[58:61], v[150:153], v[206:209], v[58:61]
	v_mfma_f32_16x16x32_bf16 v[62:65], v[150:153], v[210:213], v[62:65]
	ds_read_b128 v[198:201], v218 offset:128
	ds_read_b128 v[202:205], v218 offset:4224
	ds_read_b128 v[206:209], v218 offset:8320
	ds_read_b128 v[210:213], v218 offset:12416
	s_waitcnt lgkmcnt(3)
	v_mfma_f32_16x16x32_bf16 v[2:5], v[154:157], v[198:201], v[2:5]
	s_waitcnt lgkmcnt(2)
	v_mfma_f32_16x16x32_bf16 v[6:9], v[154:157], v[202:205], v[6:9]
	s_waitcnt lgkmcnt(1)
	v_mfma_f32_16x16x32_bf16 v[10:13], v[154:157], v[206:209], v[10:13]
	s_waitcnt lgkmcnt(0)
	v_mfma_f32_16x16x32_bf16 v[14:17], v[154:157], v[210:213], v[14:17]
	v_mfma_f32_16x16x32_bf16 v[18:21], v[158:161], v[198:201], v[18:21]
	v_mfma_f32_16x16x32_bf16 v[22:25], v[158:161], v[202:205], v[22:25]
	v_mfma_f32_16x16x32_bf16 v[26:29], v[158:161], v[206:209], v[26:29]
	v_mfma_f32_16x16x32_bf16 v[30:33], v[158:161], v[210:213], v[30:33]
	v_mfma_f32_16x16x32_bf16 v[34:37], v[162:165], v[198:201], v[34:37]
	v_mfma_f32_16x16x32_bf16 v[38:41], v[162:165], v[202:205], v[38:41]
	v_mfma_f32_16x16x32_bf16 v[42:45], v[162:165], v[206:209], v[42:45]
	v_mfma_f32_16x16x32_bf16 v[46:49], v[162:165], v[210:213], v[46:49]
	v_mfma_f32_16x16x32_bf16 v[50:53], v[166:169], v[198:201], v[50:53]
	v_mfma_f32_16x16x32_bf16 v[54:57], v[166:169], v[202:205], v[54:57]
	v_mfma_f32_16x16x32_bf16 v[58:61], v[166:169], v[206:209], v[58:61]
	v_mfma_f32_16x16x32_bf16 v[62:65], v[166:169], v[210:213], v[62:65]
	ds_read_b128 v[198:201], v218 offset:192
	ds_read_b128 v[202:205], v218 offset:4288
	ds_read_b128 v[206:209], v218 offset:8384
	ds_read_b128 v[210:213], v218 offset:12480
	s_waitcnt lgkmcnt(3)
; DEV unsigned pk2(float lo, float hi) { return (unsigned)f2bf(lo) | ((unsigned)f2bf(hi) << 16); }
; DEV float gelu_tanh(float x) { const float u = 0.7978845608028654f * (x + 0.044715f * x * x * x); return x * sigmoidf_(2.f * u); }
; __device__ __forceinline__ f32x4 unpk_lo(unsigned a, unsigned b) { return (f32x4){__uint_as_float(a << 16), __uint_as_float(a & 0xffff0000u), __uint_as_float(b << 16), __uint_as_float(b & 0xffff0000u)}; }
; DEV void s5_task(int l, int b, int g, int wave, int lane, LAS unsigned char* sm, unsigned char* ws, float* out, const float* dskip) {
;     ...
;     const f32x4 dd = *(const f32x4*)(dskip + l * 256 + g * 16 + 4 * fq);
; #pragma unroll
;     for (int i = 0; i < 4; ++i) { const int rt = wave + 8 * i;
; #pragma unroll
;         for (int nt = 0; nt < 4; ++nt) { const int n = nt * 16 + fr; const size_t row = (size_t)b * SEQ + 32 * n + rt;
;             const u32x2 uw = *(const u32x2*)((const bf16_t*)(ws + WS_U5) + ((size_t)g * M + row) * 16 + 4 * fq);
;             const f32x4 uu = pg8::unpk_lo(uw.x, uw.y); f32x4 y = acc[i][nt] + dd * uu;
;             u32x2 o; o.x = pk2(gelu_tanh(y[0]), gelu_tanh(y[1])); o.y = pk2(gelu_tanh(y[2]), gelu_tanh(y[3]));
;             *(u32x2*)((bf16_t*)(ws + WS_Y5) + row * 256 + g * 16 + 4 * fq) = o; } }
	v_mfma_f32_16x16x32_bf16 v[2:5], v[170:173], v[198:201], v[2:5]
	s_waitcnt lgkmcnt(2)
	v_mfma_f32_16x16x32_bf16 v[6:9], v[170:173], v[202:205], v[6:9]
	s_waitcnt lgkmcnt(1)
	v_mfma_f32_16x16x32_bf16 v[10:13], v[170:173], v[206:209], v[10:13]
	s_waitcnt lgkmcnt(0)
	v_mfma_f32_16x16x32_bf16 v[14:17], v[170:173], v[210:213], v[14:17]
	v_mfma_f32_16x16x32_bf16 v[18:21], v[174:177], v[198:201], v[18:21]
	v_mfma_f32_16x16x32_bf16 v[22:25], v[174:177], v[202:205], v[22:25]
	v_mfma_f32_16x16x32_bf16 v[26:29], v[174:177], v[206:209], v[26:29]
	v_mfma_f32_16x16x32_bf16 v[30:33], v[174:177], v[210:213], v[30:33]
	v_mfma_f32_16x16x32_bf16 v[34:37], v[178:181], v[198:201], v[34:37]
	v_mfma_f32_16x16x32_bf16 v[38:41], v[178:181], v[202:205], v[38:41]
	v_mfma_f32_16x16x32_bf16 v[42:45], v[178:181], v[206:209], v[42:45]
	v_mfma_f32_16x16x32_bf16 v[46:49], v[178:181], v[210:213], v[46:49]
	v_mfma_f32_16x16x32_bf16 v[50:53], v[182:185], v[198:201], v[50:53]
	v_mfma_f32_16x16x32_bf16 v[54:57], v[182:185], v[202:205], v[54:57]
	v_mfma_f32_16x16x32_bf16 v[58:61], v[182:185], v[206:209], v[58:61]
	v_mfma_f32_16x16x32_bf16 v[62:65], v[182:185], v[210:213], v[62:65]
	s_lshl_b32 s3, s2, 20
	s_lshl_b32 s6, s1, 5
	s_add_i32 s3, s3, s6
	s_add_u32 s6, s26, s3
	s_addc_u32 s7, s27, 0
	s_add_u32 s6, s6, 0x12758100
	s_addc_u32 s7, s7, 0
	s_waitcnt vmcnt(0)
	s_nop 4
	v_lshlrev_b32_e32 v242, 16, v82
	v_and_b32_e32 v243, 0xffff0000, v82
	v_lshlrev_b32_e32 v244, 16, v83
	v_and_b32_e32 v245, 0xffff0000, v83
	v_fma_f32 v2, v222, v242, v2
	v_fma_f32 v3, v223, v243, v3
	v_fma_f32 v4, v224, v244, v4
	v_fma_f32 v5, v225, v245, v5
	v_mul_f32_e32 v242, 0x3d372713, v2
	v_mul_f32_e32 v243, 0x3d372713, v3
	v_mul_f32_e32 v244, 0x3d372713, v4
	v_mul_f32_e32 v245, 0x3d372713, v5
	v_mul_f32_e32 v242, v2, v242
	v_mul_f32_e32 v243, v3, v243
	v_mul_f32_e32 v244, v4, v244
	v_mul_f32_e32 v245, v5, v245
	v_fma_f32 v242, v2, v242, v2
	v_fma_f32 v243, v3, v243, v3
	v_fma_f32 v244, v4, v244, v4
	v_fma_f32 v245, v5, v245, v5
	v_mul_f32_e32 v242, 0x3f4c422a, v242
	v_mul_f32_e32 v243, 0x3f4c422a, v243
	v_mul_f32_e32 v244, 0x3f4c422a, v244
	v_mul_f32_e32 v245, 0x3f4c422a, v245
	v_add_f32_e32 v242, v242, v242
	v_add_f32_e32 v243, v243, v243
	v_add_f32_e32 v244, v244, v244
	v_add_f32_e32 v245, v245, v245
	v_mul_f32_e32 v242, 0xbfb8aa3b, v242
	v_mul_f32_e32 v243, 0xbfb8aa3b, v243
	v_mul_f32_e32 v244, 0xbfb8aa3b, v244
	v_mul_f32_e32 v245, 0xbfb8aa3b, v245
	v_exp_f32_e32 v242, v242
	v_exp_f32_e32 v243, v243
	v_exp_f32_e32 v244, v244
	v_exp_f32_e32 v245, v245
	v_add_f32_e32 v242, 1.0, v242
	v_add_f32_e32 v243, 1.0, v243
	v_add_f32_e32 v244, 1.0, v244
	v_add_f32_e32 v245, 1.0, v245
	v_rcp_f32_e32 v242, v242
	v_rcp_f32_e32 v243, v243
	v_rcp_f32_e32 v244, v244
	v_rcp_f32_e32 v245, v245
	v_mul_f32_e32 v242, v2, v242
	v_mul_f32_e32 v243, v3, v243
	v_mul_f32_e32 v244, v4, v244
	v_mul_f32_e32 v245, v5, v245
	v_cvt_pk_bf16_f32 v248, v242, v243
	v_cvt_pk_bf16_f32 v249, v244, v245
	v_add_u32_e32 v220, 0x0, v219
	global_store_dwordx2 v220, v[248:249], s[6:7]
	v_lshlrev_b32_e32 v242, 16, v84
	v_and_b32_e32 v243, 0xffff0000, v84
	v_lshlrev_b32_e32 v244, 16, v85
	v_and_b32_e32 v245, 0xffff0000, v85
	v_fma_f32 v6, v222, v242, v6
	v_fma_f32 v7, v223, v243, v7
	v_fma_f32 v8, v224, v244, v8
	v_fma_f32 v9, v225, v245, v9
	v_mul_f32_e32 v242, 0x3d372713, v6
	v_mul_f32_e32 v243, 0x3d372713, v7
	v_mul_f32_e32 v244, 0x3d372713, v8
	v_mul_f32_e32 v245, 0x3d372713, v9
	v_mul_f32_e32 v242, v6, v242
	v_mul_f32_e32 v243, v7, v243
	v_mul_f32_e32 v244, v8, v244
	v_mul_f32_e32 v245, v9, v245
	v_fma_f32 v242, v6, v242, v6
	v_fma_f32 v243, v7, v243, v7
	v_fma_f32 v244, v8, v244, v8
	v_fma_f32 v245, v9, v245, v9
	v_mul_f32_e32 v242, 0x3f4c422a, v242
	v_mul_f32_e32 v243, 0x3f4c422a, v243
	v_mul_f32_e32 v244, 0x3f4c422a, v244
	v_mul_f32_e32 v245, 0x3f4c422a, v245
	v_add_f32_e32 v242, v242, v242
	v_add_f32_e32 v243, v243, v243
	v_add_f32_e32 v244, v244, v244
	v_add_f32_e32 v245, v245, v245
	v_mul_f32_e32 v242, 0xbfb8aa3b, v242
	v_mul_f32_e32 v243, 0xbfb8aa3b, v243
	v_mul_f32_e32 v244, 0xbfb8aa3b, v244
	v_mul_f32_e32 v245, 0xbfb8aa3b, v245
	v_exp_f32_e32 v242, v242
	v_exp_f32_e32 v243, v243
	v_exp_f32_e32 v244, v244
	v_exp_f32_e32 v245, v245
	v_add_f32_e32 v242, 1.0, v242
	v_add_f32_e32 v243, 1.0, v243
	v_add_f32_e32 v244, 1.0, v244
	v_add_f32_e32 v245, 1.0, v245
	v_rcp_f32_e32 v242, v242
	v_rcp_f32_e32 v243, v243
	v_rcp_f32_e32 v244, v244
	v_rcp_f32_e32 v245, v245
	v_mul_f32_e32 v242, v6, v242
	v_mul_f32_e32 v243, v7, v243
	v_mul_f32_e32 v244, v8, v244
	v_mul_f32_e32 v245, v9, v245
	v_cvt_pk_bf16_f32 v248, v242, v243
	v_cvt_pk_bf16_f32 v249, v244, v245
	v_add_u32_e32 v220, 0x40000, v219
	global_store_dwordx2 v220, v[248:249], s[6:7]
	v_lshlrev_b32_e32 v242, 16, v86
	v_and_b32_e32 v243, 0xffff0000, v86
	v_lshlrev_b32_e32 v244, 16, v87
	v_and_b32_e32 v245, 0xffff0000, v87
	v_fma_f32 v10, v222, v242, v10
	v_fma_f32 v11, v223, v243, v11
	v_fma_f32 v12, v224, v244, v12
	v_fma_f32 v13, v225, v245, v13
	v_mul_f32_e32 v242, 0x3d372713, v10
	v_mul_f32_e32 v243, 0x3d372713, v11
	v_mul_f32_e32 v244, 0x3d372713, v12
	v_mul_f32_e32 v245, 0x3d372713, v13
	v_mul_f32_e32 v242, v10, v242
	v_mul_f32_e32 v243, v11, v243
	v_mul_f32_e32 v244, v12, v244
	v_mul_f32_e32 v245, v13, v245
	v_fma_f32 v242, v10, v242, v10
	v_fma_f32 v243, v11, v243, v11
	v_fma_f32 v244, v12, v244, v12
	v_fma_f32 v245, v13, v245, v13
	v_mul_f32_e32 v242, 0x3f4c422a, v242
	v_mul_f32_e32 v243, 0x3f4c422a, v243
	v_mul_f32_e32 v244, 0x3f4c422a, v244
	v_mul_f32_e32 v245, 0x3f4c422a, v245
	v_add_f32_e32 v242, v242, v242
	v_add_f32_e32 v243, v243, v243
	v_add_f32_e32 v244, v244, v244
; DEV unsigned pk2(float lo, float hi) { return (unsigned)f2bf(lo) | ((unsigned)f2bf(hi) << 16); }
; DEV float gelu_tanh(float x) { const float u = 0.7978845608028654f * (x + 0.044715f * x * x * x); return x * sigmoidf_(2.f * u); }
; __device__ __forceinline__ f32x4 unpk_lo(unsigned a, unsigned b) { return (f32x4){__uint_as_float(a << 16), __uint_as_float(a & 0xffff0000u), __uint_as_float(b << 16), __uint_as_float(b & 0xffff0000u)}; }
; DEV void s5_task(int l, int b, int g, int wave, int lane, LAS unsigned char* sm, unsigned char* ws, float* out, const float* dskip) {
;     ...
; #pragma unroll
;         for (int nt = 0; nt < 4; ++nt) { const int n = nt * 16 + fr; const size_t row = (size_t)b * SEQ + 32 * n + rt;
;             const u32x2 uw = *(const u32x2*)((const bf16_t*)(ws + WS_U5) + ((size_t)g * M + row) * 16 + 4 * fq);
;             const f32x4 uu = pg8::unpk_lo(uw.x, uw.y); f32x4 y = acc[i][nt] + dd * uu;
;             u32x2 o; o.x = pk2(gelu_tanh(y[0]), gelu_tanh(y[1])); o.y = pk2(gelu_tanh(y[2]), gelu_tanh(y[3]));
;             *(u32x2*)((bf16_t*)(ws + WS_Y5) + row * 256 + g * 16 + 4 * fq) = o; } }
	v_add_f32_e32 v245, v245, v245
	v_mul_f32_e32 v242, 0xbfb8aa3b, v242
	v_mul_f32_e32 v243, 0xbfb8aa3b, v243
	v_mul_f32_e32 v244, 0xbfb8aa3b, v244
	v_mul_f32_e32 v245, 0xbfb8aa3b, v245
	v_exp_f32_e32 v242, v242
	v_exp_f32_e32 v243, v243
	v_exp_f32_e32 v244, v244
	v_exp_f32_e32 v245, v245
	v_add_f32_e32 v242, 1.0, v242
	v_add_f32_e32 v243, 1.0, v243
	v_add_f32_e32 v244, 1.0, v244
	v_add_f32_e32 v245, 1.0, v245
	v_rcp_f32_e32 v242, v242
	v_rcp_f32_e32 v243, v243
	v_rcp_f32_e32 v244, v244
	v_rcp_f32_e32 v245, v245
	v_mul_f32_e32 v242, v10, v242
	v_mul_f32_e32 v243, v11, v243
	v_mul_f32_e32 v244, v12, v244
	v_mul_f32_e32 v245, v13, v245
	v_cvt_pk_bf16_f32 v248, v242, v243
	v_cvt_pk_bf16_f32 v249, v244, v245
	v_add_u32_e32 v220, 0x80000, v219
	global_store_dwordx2 v220, v[248:249], s[6:7]
	v_lshlrev_b32_e32 v242, 16, v88
	v_and_b32_e32 v243, 0xffff0000, v88
	v_lshlrev_b32_e32 v244, 16, v89
	v_and_b32_e32 v245, 0xffff0000, v89
	v_fma_f32 v14, v222, v242, v14
	v_fma_f32 v15, v223, v243, v15
	v_fma_f32 v16, v224, v244, v16
	v_fma_f32 v17, v225, v245, v17
	v_mul_f32_e32 v242, 0x3d372713, v14
	v_mul_f32_e32 v243, 0x3d372713, v15
	v_mul_f32_e32 v244, 0x3d372713, v16
	v_mul_f32_e32 v245, 0x3d372713, v17
	v_mul_f32_e32 v242, v14, v242
	v_mul_f32_e32 v243, v15, v243
	v_mul_f32_e32 v244, v16, v244
	v_mul_f32_e32 v245, v17, v245
	v_fma_f32 v242, v14, v242, v14
	v_fma_f32 v243, v15, v243, v15
	v_fma_f32 v244, v16, v244, v16
	v_fma_f32 v245, v17, v245, v17
	v_mul_f32_e32 v242, 0x3f4c422a, v242
	v_mul_f32_e32 v243, 0x3f4c422a, v243
	v_mul_f32_e32 v244, 0x3f4c422a, v244
	v_mul_f32_e32 v245, 0x3f4c422a, v245
	v_add_f32_e32 v242, v242, v242
	v_add_f32_e32 v243, v243, v243
	v_add_f32_e32 v244, v244, v244
	v_add_f32_e32 v245, v245, v245
	v_mul_f32_e32 v242, 0xbfb8aa3b, v242
	v_mul_f32_e32 v243, 0xbfb8aa3b, v243
	v_mul_f32_e32 v244, 0xbfb8aa3b, v244
	v_mul_f32_e32 v245, 0xbfb8aa3b, v245
	v_exp_f32_e32 v242, v242
	v_exp_f32_e32 v243, v243
	v_exp_f32_e32 v244, v244
	v_exp_f32_e32 v245, v245
	v_add_f32_e32 v242, 1.0, v242
	v_add_f32_e32 v243, 1.0, v243
	v_add_f32_e32 v244, 1.0, v244
	v_add_f32_e32 v245, 1.0, v245
	v_rcp_f32_e32 v242, v242
	v_rcp_f32_e32 v243, v243
	v_rcp_f32_e32 v244, v244
	v_rcp_f32_e32 v245, v245
	v_mul_f32_e32 v242, v14, v242
	v_mul_f32_e32 v243, v15, v243
	v_mul_f32_e32 v244, v16, v244
	v_mul_f32_e32 v245, v17, v245
	v_cvt_pk_bf16_f32 v248, v242, v243
	v_cvt_pk_bf16_f32 v249, v244, v245
	v_add_u32_e32 v220, 0xc0000, v219
	global_store_dwordx2 v220, v[248:249], s[6:7]
	v_lshlrev_b32_e32 v242, 16, v90
	v_and_b32_e32 v243, 0xffff0000, v90
	v_lshlrev_b32_e32 v244, 16, v91
	v_and_b32_e32 v245, 0xffff0000, v91
	v_fma_f32 v18, v222, v242, v18
	v_fma_f32 v19, v223, v243, v19
	v_fma_f32 v20, v224, v244, v20
	v_fma_f32 v21, v225, v245, v21
	v_mul_f32_e32 v242, 0x3d372713, v18
	v_mul_f32_e32 v243, 0x3d372713, v19
	v_mul_f32_e32 v244, 0x3d372713, v20
	v_mul_f32_e32 v245, 0x3d372713, v21
	v_mul_f32_e32 v242, v18, v242
	v_mul_f32_e32 v243, v19, v243
	v_mul_f32_e32 v244, v20, v244
	v_mul_f32_e32 v245, v21, v245
	v_fma_f32 v242, v18, v242, v18
	v_fma_f32 v243, v19, v243, v19
	v_fma_f32 v244, v20, v244, v20
	v_fma_f32 v245, v21, v245, v21
	v_mul_f32_e32 v242, 0x3f4c422a, v242
	v_mul_f32_e32 v243, 0x3f4c422a, v243
	v_mul_f32_e32 v244, 0x3f4c422a, v244
	v_mul_f32_e32 v245, 0x3f4c422a, v245
	v_add_f32_e32 v242, v242, v242
	v_add_f32_e32 v243, v243, v243
	v_add_f32_e32 v244, v244, v244
	v_add_f32_e32 v245, v245, v245
	v_mul_f32_e32 v242, 0xbfb8aa3b, v242
	v_mul_f32_e32 v243, 0xbfb8aa3b, v243
	v_mul_f32_e32 v244, 0xbfb8aa3b, v244
	v_mul_f32_e32 v245, 0xbfb8aa3b, v245
	v_exp_f32_e32 v242, v242
	v_exp_f32_e32 v243, v243
	v_exp_f32_e32 v244, v244
	v_exp_f32_e32 v245, v245
	v_add_f32_e32 v242, 1.0, v242
	v_add_f32_e32 v243, 1.0, v243
	v_add_f32_e32 v244, 1.0, v244
	v_add_f32_e32 v245, 1.0, v245
	v_rcp_f32_e32 v242, v242
	v_rcp_f32_e32 v243, v243
	v_rcp_f32_e32 v244, v244
	v_rcp_f32_e32 v245, v245
	v_mul_f32_e32 v242, v18, v242
	v_mul_f32_e32 v243, v19, v243
	v_mul_f32_e32 v244, v20, v244
	v_mul_f32_e32 v245, v21, v245
	v_cvt_pk_bf16_f32 v248, v242, v243
	v_cvt_pk_bf16_f32 v249, v244, v245
	v_add_u32_e32 v220, 0x1000, v219
	global_store_dwordx2 v220, v[248:249], s[6:7]
	v_lshlrev_b32_e32 v242, 16, v92
	v_and_b32_e32 v243, 0xffff0000, v92
	v_lshlrev_b32_e32 v244, 16, v93
	v_and_b32_e32 v245, 0xffff0000, v93
	v_fma_f32 v22, v222, v242, v22
	v_fma_f32 v23, v223, v243, v23
	v_fma_f32 v24, v224, v244, v24
	v_fma_f32 v25, v225, v245, v25
	v_mul_f32_e32 v242, 0x3d372713, v22
	v_mul_f32_e32 v243, 0x3d372713, v23
	v_mul_f32_e32 v244, 0x3d372713, v24
	v_mul_f32_e32 v245, 0x3d372713, v25
	v_mul_f32_e32 v242, v22, v242
	v_mul_f32_e32 v243, v23, v243
	v_mul_f32_e32 v244, v24, v244
	v_mul_f32_e32 v245, v25, v245
	v_fma_f32 v242, v22, v242, v22
	v_fma_f32 v243, v23, v243, v23
	v_fma_f32 v244, v24, v244, v24
	v_fma_f32 v245, v25, v245, v25
	v_mul_f32_e32 v242, 0x3f4c422a, v242
	v_mul_f32_e32 v243, 0x3f4c422a, v243
	v_mul_f32_e32 v244, 0x3f4c422a, v244
	v_mul_f32_e32 v245, 0x3f4c422a, v245
	v_add_f32_e32 v242, v242, v242
	v_add_f32_e32 v243, v243, v243
	v_add_f32_e32 v244, v244, v244
	v_add_f32_e32 v245, v245, v245
	v_mul_f32_e32 v242, 0xbfb8aa3b, v242
	v_mul_f32_e32 v243, 0xbfb8aa3b, v243
	v_mul_f32_e32 v244, 0xbfb8aa3b, v244
	v_mul_f32_e32 v245, 0xbfb8aa3b, v245
	v_exp_f32_e32 v242, v242
	v_exp_f32_e32 v243, v243
	v_exp_f32_e32 v244, v244
	v_exp_f32_e32 v245, v245
	v_add_f32_e32 v242, 1.0, v242
	v_add_f32_e32 v243, 1.0, v243
	v_add_f32_e32 v244, 1.0, v244
	v_add_f32_e32 v245, 1.0, v245
	v_rcp_f32_e32 v242, v242
	v_rcp_f32_e32 v243, v243
	v_rcp_f32_e32 v244, v244
	v_rcp_f32_e32 v245, v245
; DEV unsigned pk2(float lo, float hi) { return (unsigned)f2bf(lo) | ((unsigned)f2bf(hi) << 16); }
; DEV float gelu_tanh(float x) { const float u = 0.7978845608028654f * (x + 0.044715f * x * x * x); return x * sigmoidf_(2.f * u); }
; __device__ __forceinline__ f32x4 unpk_lo(unsigned a, unsigned b) { return (f32x4){__uint_as_float(a << 16), __uint_as_float(a & 0xffff0000u), __uint_as_float(b << 16), __uint_as_float(b & 0xffff0000u)}; }
; DEV void s5_task(int l, int b, int g, int wave, int lane, LAS unsigned char* sm, unsigned char* ws, float* out, const float* dskip) {
;     ...
; #pragma unroll
;         for (int nt = 0; nt < 4; ++nt) { const int n = nt * 16 + fr; const size_t row = (size_t)b * SEQ + 32 * n + rt;
;             const u32x2 uw = *(const u32x2*)((const bf16_t*)(ws + WS_U5) + ((size_t)g * M + row) * 16 + 4 * fq);
;             const f32x4 uu = pg8::unpk_lo(uw.x, uw.y); f32x4 y = acc[i][nt] + dd * uu;
;             u32x2 o; o.x = pk2(gelu_tanh(y[0]), gelu_tanh(y[1])); o.y = pk2(gelu_tanh(y[2]), gelu_tanh(y[3]));
;             *(u32x2*)((bf16_t*)(ws + WS_Y5) + row * 256 + g * 16 + 4 * fq) = o; } }
	v_mul_f32_e32 v242, v22, v242
	v_mul_f32_e32 v243, v23, v243
	v_mul_f32_e32 v244, v24, v244
	v_mul_f32_e32 v245, v25, v245
	v_cvt_pk_bf16_f32 v248, v242, v243
	v_cvt_pk_bf16_f32 v249, v244, v245
	v_add_u32_e32 v220, 0x41000, v219
	global_store_dwordx2 v220, v[248:249], s[6:7]
	v_lshlrev_b32_e32 v242, 16, v94
	v_and_b32_e32 v243, 0xffff0000, v94
	v_lshlrev_b32_e32 v244, 16, v95
	v_and_b32_e32 v245, 0xffff0000, v95
	v_fma_f32 v26, v222, v242, v26
	v_fma_f32 v27, v223, v243, v27
	v_fma_f32 v28, v224, v244, v28
	v_fma_f32 v29, v225, v245, v29
	v_mul_f32_e32 v242, 0x3d372713, v26
	v_mul_f32_e32 v243, 0x3d372713, v27
	v_mul_f32_e32 v244, 0x3d372713, v28
	v_mul_f32_e32 v245, 0x3d372713, v29
	v_mul_f32_e32 v242, v26, v242
	v_mul_f32_e32 v243, v27, v243
	v_mul_f32_e32 v244, v28, v244
	v_mul_f32_e32 v245, v29, v245
	v_fma_f32 v242, v26, v242, v26
	v_fma_f32 v243, v27, v243, v27
	v_fma_f32 v244, v28, v244, v28
	v_fma_f32 v245, v29, v245, v29
	v_mul_f32_e32 v242, 0x3f4c422a, v242
	v_mul_f32_e32 v243, 0x3f4c422a, v243
	v_mul_f32_e32 v244, 0x3f4c422a, v244
	v_mul_f32_e32 v245, 0x3f4c422a, v245
	v_add_f32_e32 v242, v242, v242
	v_add_f32_e32 v243, v243, v243
	v_add_f32_e32 v244, v244, v244
	v_add_f32_e32 v245, v245, v245
	v_mul_f32_e32 v242, 0xbfb8aa3b, v242
	v_mul_f32_e32 v243, 0xbfb8aa3b, v243
	v_mul_f32_e32 v244, 0xbfb8aa3b, v244
	v_mul_f32_e32 v245, 0xbfb8aa3b, v245
	v_exp_f32_e32 v242, v242
	v_exp_f32_e32 v243, v243
	v_exp_f32_e32 v244, v244
	v_exp_f32_e32 v245, v245
	v_add_f32_e32 v242, 1.0, v242
	v_add_f32_e32 v243, 1.0, v243
	v_add_f32_e32 v244, 1.0, v244
	v_add_f32_e32 v245, 1.0, v245
	v_rcp_f32_e32 v242, v242
	v_rcp_f32_e32 v243, v243
	v_rcp_f32_e32 v244, v244
	v_rcp_f32_e32 v245, v245
	v_mul_f32_e32 v242, v26, v242
	v_mul_f32_e32 v243, v27, v243
	v_mul_f32_e32 v244, v28, v244
	v_mul_f32_e32 v245, v29, v245
	v_cvt_pk_bf16_f32 v248, v242, v243
	v_cvt_pk_bf16_f32 v249, v244, v245
	v_add_u32_e32 v220, 0x81000, v219
	global_store_dwordx2 v220, v[248:249], s[6:7]
	v_lshlrev_b32_e32 v242, 16, v96
	v_and_b32_e32 v243, 0xffff0000, v96
	v_lshlrev_b32_e32 v244, 16, v97
	v_and_b32_e32 v245, 0xffff0000, v97
	v_fma_f32 v30, v222, v242, v30
	v_fma_f32 v31, v223, v243, v31
	v_fma_f32 v32, v224, v244, v32
	v_fma_f32 v33, v225, v245, v33
	v_mul_f32_e32 v242, 0x3d372713, v30
	v_mul_f32_e32 v243, 0x3d372713, v31
	v_mul_f32_e32 v244, 0x3d372713, v32
	v_mul_f32_e32 v245, 0x3d372713, v33
	v_mul_f32_e32 v242, v30, v242
	v_mul_f32_e32 v243, v31, v243
	v_mul_f32_e32 v244, v32, v244
	v_mul_f32_e32 v245, v33, v245
	v_fma_f32 v242, v30, v242, v30
	v_fma_f32 v243, v31, v243, v31
	v_fma_f32 v244, v32, v244, v32
	v_fma_f32 v245, v33, v245, v33
	v_mul_f32_e32 v242, 0x3f4c422a, v242
	v_mul_f32_e32 v243, 0x3f4c422a, v243
	v_mul_f32_e32 v244, 0x3f4c422a, v244
	v_mul_f32_e32 v245, 0x3f4c422a, v245
	v_add_f32_e32 v242, v242, v242
	v_add_f32_e32 v243, v243, v243
	v_add_f32_e32 v244, v244, v244
	v_add_f32_e32 v245, v245, v245
	v_mul_f32_e32 v242, 0xbfb8aa3b, v242
	v_mul_f32_e32 v243, 0xbfb8aa3b, v243
	v_mul_f32_e32 v244, 0xbfb8aa3b, v244
	v_mul_f32_e32 v245, 0xbfb8aa3b, v245
	v_exp_f32_e32 v242, v242
	v_exp_f32_e32 v243, v243
	v_exp_f32_e32 v244, v244
	v_exp_f32_e32 v245, v245
	v_add_f32_e32 v242, 1.0, v242
	v_add_f32_e32 v243, 1.0, v243
	v_add_f32_e32 v244, 1.0, v244
	v_add_f32_e32 v245, 1.0, v245
	v_rcp_f32_e32 v242, v242
	v_rcp_f32_e32 v243, v243
	v_rcp_f32_e32 v244, v244
	v_rcp_f32_e32 v245, v245
	v_mul_f32_e32 v242, v30, v242
	v_mul_f32_e32 v243, v31, v243
	v_mul_f32_e32 v244, v32, v244
	v_mul_f32_e32 v245, v33, v245
	v_cvt_pk_bf16_f32 v248, v242, v243
	v_cvt_pk_bf16_f32 v249, v244, v245
	v_add_u32_e32 v220, 0xc1000, v219
	global_store_dwordx2 v220, v[248:249], s[6:7]
	v_lshlrev_b32_e32 v242, 16, v98
	v_and_b32_e32 v243, 0xffff0000, v98
	v_lshlrev_b32_e32 v244, 16, v99
	v_and_b32_e32 v245, 0xffff0000, v99
	v_fma_f32 v34, v222, v242, v34
	v_fma_f32 v35, v223, v243, v35
	v_fma_f32 v36, v224, v244, v36
	v_fma_f32 v37, v225, v245, v37
	v_mul_f32_e32 v242, 0x3d372713, v34
	v_mul_f32_e32 v243, 0x3d372713, v35
	v_mul_f32_e32 v244, 0x3d372713, v36
	v_mul_f32_e32 v245, 0x3d372713, v37
	v_mul_f32_e32 v242, v34, v242
	v_mul_f32_e32 v243, v35, v243
	v_mul_f32_e32 v244, v36, v244
	v_mul_f32_e32 v245, v37, v245
	v_fma_f32 v242, v34, v242, v34
	v_fma_f32 v243, v35, v243, v35
	v_fma_f32 v244, v36, v244, v36
	v_fma_f32 v245, v37, v245, v37
	v_mul_f32_e32 v242, 0x3f4c422a, v242
	v_mul_f32_e32 v243, 0x3f4c422a, v243
	v_mul_f32_e32 v244, 0x3f4c422a, v244
	v_mul_f32_e32 v245, 0x3f4c422a, v245
	v_add_f32_e32 v242, v242, v242
	v_add_f32_e32 v243, v243, v243
	v_add_f32_e32 v244, v244, v244
	v_add_f32_e32 v245, v245, v245
	v_mul_f32_e32 v242, 0xbfb8aa3b, v242
	v_mul_f32_e32 v243, 0xbfb8aa3b, v243
	v_mul_f32_e32 v244, 0xbfb8aa3b, v244
	v_mul_f32_e32 v245, 0xbfb8aa3b, v245
	v_exp_f32_e32 v242, v242
	v_exp_f32_e32 v243, v243
	v_exp_f32_e32 v244, v244
	v_exp_f32_e32 v245, v245
	v_add_f32_e32 v242, 1.0, v242
	v_add_f32_e32 v243, 1.0, v243
	v_add_f32_e32 v244, 1.0, v244
	v_add_f32_e32 v245, 1.0, v245
	v_rcp_f32_e32 v242, v242
	v_rcp_f32_e32 v243, v243
	v_rcp_f32_e32 v244, v244
	v_rcp_f32_e32 v245, v245
	v_mul_f32_e32 v242, v34, v242
	v_mul_f32_e32 v243, v35, v243
	v_mul_f32_e32 v244, v36, v244
	v_mul_f32_e32 v245, v37, v245
	v_cvt_pk_bf16_f32 v248, v242, v243
	v_cvt_pk_bf16_f32 v249, v244, v245
	v_add_u32_e32 v220, 0x2000, v219
	global_store_dwordx2 v220, v[248:249], s[6:7]
	v_lshlrev_b32_e32 v242, 16, v100
	v_and_b32_e32 v243, 0xffff0000, v100
	v_lshlrev_b32_e32 v244, 16, v101
	v_and_b32_e32 v245, 0xffff0000, v101
	v_fma_f32 v38, v222, v242, v38
	v_fma_f32 v39, v223, v243, v39
	v_fma_f32 v40, v224, v244, v40
; DEV unsigned pk2(float lo, float hi) { return (unsigned)f2bf(lo) | ((unsigned)f2bf(hi) << 16); }
; DEV float gelu_tanh(float x) { const float u = 0.7978845608028654f * (x + 0.044715f * x * x * x); return x * sigmoidf_(2.f * u); }
; __device__ __forceinline__ f32x4 unpk_lo(unsigned a, unsigned b) { return (f32x4){__uint_as_float(a << 16), __uint_as_float(a & 0xffff0000u), __uint_as_float(b << 16), __uint_as_float(b & 0xffff0000u)}; }
; DEV void s5_task(int l, int b, int g, int wave, int lane, LAS unsigned char* sm, unsigned char* ws, float* out, const float* dskip) {
;     ...
; #pragma unroll
;         for (int nt = 0; nt < 4; ++nt) { const int n = nt * 16 + fr; const size_t row = (size_t)b * SEQ + 32 * n + rt;
;             const u32x2 uw = *(const u32x2*)((const bf16_t*)(ws + WS_U5) + ((size_t)g * M + row) * 16 + 4 * fq);
;             const f32x4 uu = pg8::unpk_lo(uw.x, uw.y); f32x4 y = acc[i][nt] + dd * uu;
;             u32x2 o; o.x = pk2(gelu_tanh(y[0]), gelu_tanh(y[1])); o.y = pk2(gelu_tanh(y[2]), gelu_tanh(y[3]));
;             *(u32x2*)((bf16_t*)(ws + WS_Y5) + row * 256 + g * 16 + 4 * fq) = o; } }
	v_fma_f32 v41, v225, v245, v41
	v_mul_f32_e32 v242, 0x3d372713, v38
	v_mul_f32_e32 v243, 0x3d372713, v39
	v_mul_f32_e32 v244, 0x3d372713, v40
	v_mul_f32_e32 v245, 0x3d372713, v41
	v_mul_f32_e32 v242, v38, v242
	v_mul_f32_e32 v243, v39, v243
	v_mul_f32_e32 v244, v40, v244
	v_mul_f32_e32 v245, v41, v245
	v_fma_f32 v242, v38, v242, v38
	v_fma_f32 v243, v39, v243, v39
	v_fma_f32 v244, v40, v244, v40
	v_fma_f32 v245, v41, v245, v41
	v_mul_f32_e32 v242, 0x3f4c422a, v242
	v_mul_f32_e32 v243, 0x3f4c422a, v243
	v_mul_f32_e32 v244, 0x3f4c422a, v244
	v_mul_f32_e32 v245, 0x3f4c422a, v245
	v_add_f32_e32 v242, v242, v242
	v_add_f32_e32 v243, v243, v243
	v_add_f32_e32 v244, v244, v244
	v_add_f32_e32 v245, v245, v245
	v_mul_f32_e32 v242, 0xbfb8aa3b, v242
	v_mul_f32_e32 v243, 0xbfb8aa3b, v243
	v_mul_f32_e32 v244, 0xbfb8aa3b, v244
	v_mul_f32_e32 v245, 0xbfb8aa3b, v245
	v_exp_f32_e32 v242, v242
	v_exp_f32_e32 v243, v243
	v_exp_f32_e32 v244, v244
	v_exp_f32_e32 v245, v245
	v_add_f32_e32 v242, 1.0, v242
	v_add_f32_e32 v243, 1.0, v243
	v_add_f32_e32 v244, 1.0, v244
	v_add_f32_e32 v245, 1.0, v245
	v_rcp_f32_e32 v242, v242
	v_rcp_f32_e32 v243, v243
	v_rcp_f32_e32 v244, v244
	v_rcp_f32_e32 v245, v245
	v_mul_f32_e32 v242, v38, v242
	v_mul_f32_e32 v243, v39, v243
	v_mul_f32_e32 v244, v40, v244
	v_mul_f32_e32 v245, v41, v245
	v_cvt_pk_bf16_f32 v248, v242, v243
	v_cvt_pk_bf16_f32 v249, v244, v245
	v_add_u32_e32 v220, 0x42000, v219
	global_store_dwordx2 v220, v[248:249], s[6:7]
	v_lshlrev_b32_e32 v242, 16, v102
	v_and_b32_e32 v243, 0xffff0000, v102
	v_lshlrev_b32_e32 v244, 16, v103
	v_and_b32_e32 v245, 0xffff0000, v103
	v_fma_f32 v42, v222, v242, v42
	v_fma_f32 v43, v223, v243, v43
	v_fma_f32 v44, v224, v244, v44
	v_fma_f32 v45, v225, v245, v45
	v_mul_f32_e32 v242, 0x3d372713, v42
	v_mul_f32_e32 v243, 0x3d372713, v43
	v_mul_f32_e32 v244, 0x3d372713, v44
	v_mul_f32_e32 v245, 0x3d372713, v45
	v_mul_f32_e32 v242, v42, v242
	v_mul_f32_e32 v243, v43, v243
	v_mul_f32_e32 v244, v44, v244
	v_mul_f32_e32 v245, v45, v245
	v_fma_f32 v242, v42, v242, v42
	v_fma_f32 v243, v43, v243, v43
	v_fma_f32 v244, v44, v244, v44
	v_fma_f32 v245, v45, v245, v45
	v_mul_f32_e32 v242, 0x3f4c422a, v242
	v_mul_f32_e32 v243, 0x3f4c422a, v243
	v_mul_f32_e32 v244, 0x3f4c422a, v244
	v_mul_f32_e32 v245, 0x3f4c422a, v245
	v_add_f32_e32 v242, v242, v242
	v_add_f32_e32 v243, v243, v243
	v_add_f32_e32 v244, v244, v244
	v_add_f32_e32 v245, v245, v245
	v_mul_f32_e32 v242, 0xbfb8aa3b, v242
	v_mul_f32_e32 v243, 0xbfb8aa3b, v243
	v_mul_f32_e32 v244, 0xbfb8aa3b, v244
	v_mul_f32_e32 v245, 0xbfb8aa3b, v245
	v_exp_f32_e32 v242, v242
	v_exp_f32_e32 v243, v243
	v_exp_f32_e32 v244, v244
	v_exp_f32_e32 v245, v245
	v_add_f32_e32 v242, 1.0, v242
	v_add_f32_e32 v243, 1.0, v243
	v_add_f32_e32 v244, 1.0, v244
	v_add_f32_e32 v245, 1.0, v245
	v_rcp_f32_e32 v242, v242
	v_rcp_f32_e32 v243, v243
	v_rcp_f32_e32 v244, v244
	v_rcp_f32_e32 v245, v245
	v_mul_f32_e32 v242, v42, v242
	v_mul_f32_e32 v243, v43, v243
	v_mul_f32_e32 v244, v44, v244
	v_mul_f32_e32 v245, v45, v245
	v_cvt_pk_bf16_f32 v248, v242, v243
	v_cvt_pk_bf16_f32 v249, v244, v245
	v_add_u32_e32 v220, 0x82000, v219
	global_store_dwordx2 v220, v[248:249], s[6:7]
	v_lshlrev_b32_e32 v242, 16, v104
	v_and_b32_e32 v243, 0xffff0000, v104
	v_lshlrev_b32_e32 v244, 16, v105
	v_and_b32_e32 v245, 0xffff0000, v105
	v_fma_f32 v46, v222, v242, v46
	v_fma_f32 v47, v223, v243, v47
	v_fma_f32 v48, v224, v244, v48
	v_fma_f32 v49, v225, v245, v49
	v_mul_f32_e32 v242, 0x3d372713, v46
	v_mul_f32_e32 v243, 0x3d372713, v47
	v_mul_f32_e32 v244, 0x3d372713, v48
	v_mul_f32_e32 v245, 0x3d372713, v49
	v_mul_f32_e32 v242, v46, v242
	v_mul_f32_e32 v243, v47, v243
	v_mul_f32_e32 v244, v48, v244
	v_mul_f32_e32 v245, v49, v245
	v_fma_f32 v242, v46, v242, v46
	v_fma_f32 v243, v47, v243, v47
	v_fma_f32 v244, v48, v244, v48
	v_fma_f32 v245, v49, v245, v49
	v_mul_f32_e32 v242, 0x3f4c422a, v242
	v_mul_f32_e32 v243, 0x3f4c422a, v243
	v_mul_f32_e32 v244, 0x3f4c422a, v244
	v_mul_f32_e32 v245, 0x3f4c422a, v245
	v_add_f32_e32 v242, v242, v242
	v_add_f32_e32 v243, v243, v243
	v_add_f32_e32 v244, v244, v244
	v_add_f32_e32 v245, v245, v245
	v_mul_f32_e32 v242, 0xbfb8aa3b, v242
	v_mul_f32_e32 v243, 0xbfb8aa3b, v243
	v_mul_f32_e32 v244, 0xbfb8aa3b, v244
	v_mul_f32_e32 v245, 0xbfb8aa3b, v245
	v_exp_f32_e32 v242, v242
	v_exp_f32_e32 v243, v243
	v_exp_f32_e32 v244, v244
	v_exp_f32_e32 v245, v245
	v_add_f32_e32 v242, 1.0, v242
	v_add_f32_e32 v243, 1.0, v243
	v_add_f32_e32 v244, 1.0, v244
	v_add_f32_e32 v245, 1.0, v245
	v_rcp_f32_e32 v242, v242
	v_rcp_f32_e32 v243, v243
	v_rcp_f32_e32 v244, v244
	v_rcp_f32_e32 v245, v245
	v_mul_f32_e32 v242, v46, v242
	v_mul_f32_e32 v243, v47, v243
	v_mul_f32_e32 v244, v48, v244
	v_mul_f32_e32 v245, v49, v245
	v_cvt_pk_bf16_f32 v248, v242, v243
	v_cvt_pk_bf16_f32 v249, v244, v245
	v_add_u32_e32 v220, 0xc2000, v219
	global_store_dwordx2 v220, v[248:249], s[6:7]
	v_lshlrev_b32_e32 v242, 16, v106
	v_and_b32_e32 v243, 0xffff0000, v106
	v_lshlrev_b32_e32 v244, 16, v107
	v_and_b32_e32 v245, 0xffff0000, v107
	v_fma_f32 v50, v222, v242, v50
	v_fma_f32 v51, v223, v243, v51
	v_fma_f32 v52, v224, v244, v52
	v_fma_f32 v53, v225, v245, v53
	v_mul_f32_e32 v242, 0x3d372713, v50
	v_mul_f32_e32 v243, 0x3d372713, v51
	v_mul_f32_e32 v244, 0x3d372713, v52
	v_mul_f32_e32 v245, 0x3d372713, v53
	v_mul_f32_e32 v242, v50, v242
	v_mul_f32_e32 v243, v51, v243
	v_mul_f32_e32 v244, v52, v244
	v_mul_f32_e32 v245, v53, v245
	v_fma_f32 v242, v50, v242, v50
	v_fma_f32 v243, v51, v243, v51
	v_fma_f32 v244, v52, v244, v52
	v_fma_f32 v245, v53, v245, v53
	v_mul_f32_e32 v242, 0x3f4c422a, v242
	v_mul_f32_e32 v243, 0x3f4c422a, v243
; DEV unsigned pk2(float lo, float hi) { return (unsigned)f2bf(lo) | ((unsigned)f2bf(hi) << 16); }
; DEV float gelu_tanh(float x) { const float u = 0.7978845608028654f * (x + 0.044715f * x * x * x); return x * sigmoidf_(2.f * u); }
; __device__ __forceinline__ f32x4 unpk_lo(unsigned a, unsigned b) { return (f32x4){__uint_as_float(a << 16), __uint_as_float(a & 0xffff0000u), __uint_as_float(b << 16), __uint_as_float(b & 0xffff0000u)}; }
; #define KPTR(T, ap64, i) ((T*)(__attribute__((address_space(1))) T*)(ap64)[i])
; DEV void s5_task(int l, int b, int g, int wave, int lane, LAS unsigned char* sm, unsigned char* ws, float* out, const float* dskip) {
;     ...
; #pragma unroll
;         for (int nt = 0; nt < 4; ++nt) { const int n = nt * 16 + fr; const size_t row = (size_t)b * SEQ + 32 * n + rt;
;             const u32x2 uw = *(const u32x2*)((const bf16_t*)(ws + WS_U5) + ((size_t)g * M + row) * 16 + 4 * fq);
;             const f32x4 uu = pg8::unpk_lo(uw.x, uw.y); f32x4 y = acc[i][nt] + dd * uu;
;             u32x2 o; o.x = pk2(gelu_tanh(y[0]), gelu_tanh(y[1])); o.y = pk2(gelu_tanh(y[2]), gelu_tanh(y[3]));
;             *(u32x2*)((bf16_t*)(ws + WS_Y5) + row * 256 + g * 16 + 4 * fq) = o; } }
; }
; __global__ void __launch_bounds__(512, 2) mk_fwd(MKArgs args) {
;     ...
;             for (int r2_ = 0; r2_ < REP_S5 + REP_PREP - 1; ++r2_) { PHASE_IDS if (r2_ == 0 || REP_S5 > 1) for (int k = (2 * G - 33 - bx) % G; k < NB * 16; k += G) s5_task(l, k >> 4, k & 15, wave, lane, ldsl + RING_OFF, ws, out, KPTR(const float, ap, 17));
	v_mul_f32_e32 v244, 0x3f4c422a, v244
	v_mul_f32_e32 v245, 0x3f4c422a, v245
	v_add_f32_e32 v242, v242, v242
	v_add_f32_e32 v243, v243, v243
	v_add_f32_e32 v244, v244, v244
	v_add_f32_e32 v245, v245, v245
	v_mul_f32_e32 v242, 0xbfb8aa3b, v242
	v_mul_f32_e32 v243, 0xbfb8aa3b, v243
	v_mul_f32_e32 v244, 0xbfb8aa3b, v244
	v_mul_f32_e32 v245, 0xbfb8aa3b, v245
	v_exp_f32_e32 v242, v242
	v_exp_f32_e32 v243, v243
	v_exp_f32_e32 v244, v244
	v_exp_f32_e32 v245, v245
	v_add_f32_e32 v242, 1.0, v242
	v_add_f32_e32 v243, 1.0, v243
	v_add_f32_e32 v244, 1.0, v244
	v_add_f32_e32 v245, 1.0, v245
	v_rcp_f32_e32 v242, v242
	v_rcp_f32_e32 v243, v243
	v_rcp_f32_e32 v244, v244
	v_rcp_f32_e32 v245, v245
	v_mul_f32_e32 v242, v50, v242
	v_mul_f32_e32 v243, v51, v243
	v_mul_f32_e32 v244, v52, v244
	v_mul_f32_e32 v245, v53, v245
	v_cvt_pk_bf16_f32 v248, v242, v243
	v_cvt_pk_bf16_f32 v249, v244, v245
	v_add_u32_e32 v220, 0x3000, v219
	global_store_dwordx2 v220, v[248:249], s[6:7]
	v_lshlrev_b32_e32 v242, 16, v108
	v_and_b32_e32 v243, 0xffff0000, v108
	v_lshlrev_b32_e32 v244, 16, v109
	v_and_b32_e32 v245, 0xffff0000, v109
	v_fma_f32 v54, v222, v242, v54
	v_fma_f32 v55, v223, v243, v55
	v_fma_f32 v56, v224, v244, v56
	v_fma_f32 v57, v225, v245, v57
	v_mul_f32_e32 v242, 0x3d372713, v54
	v_mul_f32_e32 v243, 0x3d372713, v55
	v_mul_f32_e32 v244, 0x3d372713, v56
	v_mul_f32_e32 v245, 0x3d372713, v57
	v_mul_f32_e32 v242, v54, v242
	v_mul_f32_e32 v243, v55, v243
	v_mul_f32_e32 v244, v56, v244
	v_mul_f32_e32 v245, v57, v245
	v_fma_f32 v242, v54, v242, v54
	v_fma_f32 v243, v55, v243, v55
	v_fma_f32 v244, v56, v244, v56
	v_fma_f32 v245, v57, v245, v57
	v_mul_f32_e32 v242, 0x3f4c422a, v242
	v_mul_f32_e32 v243, 0x3f4c422a, v243
	v_mul_f32_e32 v244, 0x3f4c422a, v244
	v_mul_f32_e32 v245, 0x3f4c422a, v245
	v_add_f32_e32 v242, v242, v242
	v_add_f32_e32 v243, v243, v243
	v_add_f32_e32 v244, v244, v244
	v_add_f32_e32 v245, v245, v245
	v_mul_f32_e32 v242, 0xbfb8aa3b, v242
	v_mul_f32_e32 v243, 0xbfb8aa3b, v243
	v_mul_f32_e32 v244, 0xbfb8aa3b, v244
	v_mul_f32_e32 v245, 0xbfb8aa3b, v245
	v_exp_f32_e32 v242, v242
	v_exp_f32_e32 v243, v243
	v_exp_f32_e32 v244, v244
	v_exp_f32_e32 v245, v245
	v_add_f32_e32 v242, 1.0, v242
	v_add_f32_e32 v243, 1.0, v243
	v_add_f32_e32 v244, 1.0, v244
	v_add_f32_e32 v245, 1.0, v245
	v_rcp_f32_e32 v242, v242
	v_rcp_f32_e32 v243, v243
	v_rcp_f32_e32 v244, v244
	v_rcp_f32_e32 v245, v245
	v_mul_f32_e32 v242, v54, v242
	v_mul_f32_e32 v243, v55, v243
	v_mul_f32_e32 v244, v56, v244
	v_mul_f32_e32 v245, v57, v245
	v_cvt_pk_bf16_f32 v248, v242, v243
	v_cvt_pk_bf16_f32 v249, v244, v245
	v_add_u32_e32 v220, 0x43000, v219
	global_store_dwordx2 v220, v[248:249], s[6:7]
	v_lshlrev_b32_e32 v242, 16, v110
	v_and_b32_e32 v243, 0xffff0000, v110
	v_lshlrev_b32_e32 v244, 16, v111
	v_and_b32_e32 v245, 0xffff0000, v111
	v_fma_f32 v58, v222, v242, v58
	v_fma_f32 v59, v223, v243, v59
	v_fma_f32 v60, v224, v244, v60
	v_fma_f32 v61, v225, v245, v61
	v_mul_f32_e32 v242, 0x3d372713, v58
	v_mul_f32_e32 v243, 0x3d372713, v59
	v_mul_f32_e32 v244, 0x3d372713, v60
	v_mul_f32_e32 v245, 0x3d372713, v61
	v_mul_f32_e32 v242, v58, v242
	v_mul_f32_e32 v243, v59, v243
	v_mul_f32_e32 v244, v60, v244
	v_mul_f32_e32 v245, v61, v245
	v_fma_f32 v242, v58, v242, v58
	v_fma_f32 v243, v59, v243, v59
	v_fma_f32 v244, v60, v244, v60
	v_fma_f32 v245, v61, v245, v61
	v_mul_f32_e32 v242, 0x3f4c422a, v242
	v_mul_f32_e32 v243, 0x3f4c422a, v243
	v_mul_f32_e32 v244, 0x3f4c422a, v244
	v_mul_f32_e32 v245, 0x3f4c422a, v245
	v_add_f32_e32 v242, v242, v242
	v_add_f32_e32 v243, v243, v243
	v_add_f32_e32 v244, v244, v244
	v_add_f32_e32 v245, v245, v245
	v_mul_f32_e32 v242, 0xbfb8aa3b, v242
	v_mul_f32_e32 v243, 0xbfb8aa3b, v243
	v_mul_f32_e32 v244, 0xbfb8aa3b, v244
	v_mul_f32_e32 v245, 0xbfb8aa3b, v245
	v_exp_f32_e32 v242, v242
	v_exp_f32_e32 v243, v243
	v_exp_f32_e32 v244, v244
	v_exp_f32_e32 v245, v245
	v_add_f32_e32 v242, 1.0, v242
	v_add_f32_e32 v243, 1.0, v243
	v_add_f32_e32 v244, 1.0, v244
	v_add_f32_e32 v245, 1.0, v245
	v_rcp_f32_e32 v242, v242
	v_rcp_f32_e32 v243, v243
	v_rcp_f32_e32 v244, v244
	v_rcp_f32_e32 v245, v245
	v_mul_f32_e32 v242, v58, v242
	v_mul_f32_e32 v243, v59, v243
	v_mul_f32_e32 v244, v60, v244
	v_mul_f32_e32 v245, v61, v245
	v_cvt_pk_bf16_f32 v248, v242, v243
	v_cvt_pk_bf16_f32 v249, v244, v245
	v_add_u32_e32 v220, 0x83000, v219
	global_store_dwordx2 v220, v[248:249], s[6:7]
	v_lshlrev_b32_e32 v242, 16, v112
	v_and_b32_e32 v243, 0xffff0000, v112
	v_lshlrev_b32_e32 v244, 16, v113
	v_and_b32_e32 v245, 0xffff0000, v113
	v_fma_f32 v62, v222, v242, v62
	v_fma_f32 v63, v223, v243, v63
	v_fma_f32 v64, v224, v244, v64
	v_fma_f32 v65, v225, v245, v65
	v_mul_f32_e32 v242, 0x3d372713, v62
	v_mul_f32_e32 v243, 0x3d372713, v63
	v_mul_f32_e32 v244, 0x3d372713, v64
	v_mul_f32_e32 v245, 0x3d372713, v65
	v_mul_f32_e32 v242, v62, v242
	v_mul_f32_e32 v243, v63, v243
	v_mul_f32_e32 v244, v64, v244
	v_mul_f32_e32 v245, v65, v245
	v_fma_f32 v242, v62, v242, v62
	v_fma_f32 v243, v63, v243, v63
	v_fma_f32 v244, v64, v244, v64
	v_fma_f32 v245, v65, v245, v65
	v_mul_f32_e32 v242, 0x3f4c422a, v242
	v_mul_f32_e32 v243, 0x3f4c422a, v243
	v_mul_f32_e32 v244, 0x3f4c422a, v244
	v_mul_f32_e32 v245, 0x3f4c422a, v245
	v_add_f32_e32 v242, v242, v242
	v_add_f32_e32 v243, v243, v243
	v_add_f32_e32 v244, v244, v244
	v_add_f32_e32 v245, v245, v245
	v_mul_f32_e32 v242, 0xbfb8aa3b, v242
	v_mul_f32_e32 v243, 0xbfb8aa3b, v243
	v_mul_f32_e32 v244, 0xbfb8aa3b, v244
	v_mul_f32_e32 v245, 0xbfb8aa3b, v245
	v_exp_f32_e32 v242, v242
	v_exp_f32_e32 v243, v243
	v_exp_f32_e32 v244, v244
	v_exp_f32_e32 v245, v245
	v_add_f32_e32 v242, 1.0, v242
	v_add_f32_e32 v243, 1.0, v243
	v_add_f32_e32 v244, 1.0, v244
	v_add_f32_e32 v245, 1.0, v245
	v_rcp_f32_e32 v242, v242
	v_rcp_f32_e32 v243, v243
	v_rcp_f32_e32 v244, v244
	v_rcp_f32_e32 v245, v245
	v_mul_f32_e32 v242, v62, v242
	v_mul_f32_e32 v243, v63, v243
	v_mul_f32_e32 v244, v64, v244
	v_mul_f32_e32 v245, v65, v245
	v_cvt_pk_bf16_f32 v248, v242, v243
	v_cvt_pk_bf16_f32 v249, v244, v245
	v_add_u32_e32 v220, 0xc3000, v219
	global_store_dwordx2 v220, v[248:249], s[6:7]
	s_add_i32 s20, s20, s0
	s_cmpk_lt_i32 s20, 0x80
	s_cbranch_scc1 .Ls5s_task
	s_branch .LBB0_1023
